# GEMM K-loops without s_setprio flips (equal priority for the MFMA and the loading wave), 4/4 LDS-DMA staging, saddr DMA; attention load hoist
# baseline (speedup 1.0000x reference)
; #define PG8_STAGE(bufoff, gbase, voff) do { _Pragma("unroll") for (int _i = 0; _i < 2; ++_i) \
;         __builtin_amdgcn_global_load_lds((const unsigned*)((const char*)(gbase) + (voff)[_i]), (LAS unsigned*)(lds + (bufoff) + ldsw + _i * 8192), 16, 0, 0); } while (0)
; #define PG8_LDA(dst, b, h) do { _Pragma("unroll") for (int m = 0; m < 4; ++m) _Pragma("unroll") for (int k = 0; k < 2; ++k) dst[m][k] = *(const LAS bf16x8*)(lds + PG8_SA(b, h) + aoff + m * 2048 + k * 1024); } while (0)
; #define PG8_LDB(dst, b, h) do { _Pragma("unroll") for (int n = 0; n < 2; ++n) _Pragma("unroll") for (int k = 0; k < 2; ++k) dst[n][k] = *(const LAS bf16x8*)(lds + PG8_SB(b, h) + boff + n * 2048 + k * 1024); } while (0)
; #define PG8_WAIT_V(n) asm volatile("s_waitcnt vmcnt(" #n ")" ::: "memory")
; #define PG8_WAIT_L(n) asm volatile("s_waitcnt lgkmcnt(" #n ")" ::: "memory")
; #define PG8_BAR __builtin_amdgcn_s_barrier()
; #define PG8_SCHED __builtin_amdgcn_sched_barrier(0)
; template <class Epi, class Sched, bool I8 = false>
; __device__ __forceinline__ void gemm_phase(LAS unsigned char* lds, const Gemm g, const Sched& S, const Epi& E) {
;     ...
;             const bool last = (t == nt - 2);
;             const char* a1 = cA + (size_t)(t + 1) * kstep;
;             const char* a2 = last ? nA : cA + (size_t)(t + 2) * kstep; const char* b2 = last ? nB : cB + (size_t)(t + 2) * kstep;
;             const char* a3 = a2 + kstep; const char* b3 = b2 + kstep;
;             PG8_LDB(B0, 0, 0); PG8_LDB(B1, 0, 1); PG8_SCHED; PG8_LDA(At, 0, 0); PG8_STAGE(PG8_SA(1, 1), a1 + hstepA, voffA);
;             PG8_WAIT_V(8); PG8_WAIT_L(0); PG8_BAR; PG8_MMA(0, 0, At, B0); PG8_MMA(0, 1, At, B1); PG8_BAR; PG8_SCHED;
;             PG8_LDA(At, 0, 1); PG8_STAGE(PG8_SB(0, 0), b2, voffB); PG8_STAGE(PG8_SB(0, 1), b2 + hstepB, voffB); PG8_STAGE(PG8_SA(0, 0), a2, voffA);
;             PG8_WAIT_V(8); PG8_WAIT_L(0); PG8_BAR; PG8_MMA(1, 0, At, B0); PG8_MMA(1, 1, At, B1); PG8_BAR; PG8_SCHED;
.LBB0_1169:
	ds_read_b128 v[90:93], v169
	ds_read_b128 v[98:101], v169 offset:1024
	ds_read_b128 v[172:175], v169 offset:2048
	ds_read_b128 v[176:179], v169 offset:3072
	ds_read_b128 v[180:183], v170
	ds_read_b128 v[184:187], v170 offset:1024
	ds_read_b128 v[188:191], v170 offset:2048
	ds_read_b128 v[192:195], v170 offset:3072
	s_add_u32 s22, s20, 0x4000
	s_addc_u32 s23, s21, 0
	s_cmp_eq_u32 s53, 28
	s_cselect_b32 s26, s49, s22
	s_cselect_b32 s27, s13, s23
	s_cselect_b32 s24, s50, s51
	s_cselect_b32 s25, s11, s52
	s_add_u32 s22, s26, 0x8000
	s_addc_u32 s23, s27, 0
	s_sub_u32 s98, s20, 0x4000
	s_subb_u32 s99, s21, 0
	s_mov_b32 m0, s43
	s_nop 0
	global_load_lds_dwordx4 v144, s[98:99]
	s_mov_b32 m0, s44
	s_nop 0
	global_load_lds_dwordx4 v140, s[98:99]
	s_add_i32 m0, s36, 0xc000
	ds_read_b128 v[196:199], v171
	ds_read_b128 v[200:203], v171 offset:1024
	ds_read_b128 v[204:207], v171 offset:2048
	ds_read_b128 v[208:211], v171 offset:3072
	ds_read_b128 v[212:215], v171 offset:4096
	ds_read_b128 v[216:219], v171 offset:5120
	ds_read_b128 v[220:223], v171 offset:6144
	ds_read_b128 v[224:227], v171 offset:7168
	global_load_lds_dwordx4 v148, s[20:21]
	s_add_i32 m0, s36, 0xe000
	s_nop 0
	global_load_lds_dwordx4 v150, s[20:21]
	s_waitcnt vmcnt(8)
	s_waitcnt lgkmcnt(0)
	s_barrier
	s_waitcnt lgkmcnt(0)
	v_mfma_i32_16x16x64_i8 v[134:137], v[90:93], v[196:199], v[134:137]
	v_mfma_i32_16x16x64_i8 v[130:133], v[172:175], v[196:199], v[130:133]
	v_mfma_i32_16x16x64_i8 v[118:121], v[90:93], v[204:207], v[118:121]
	v_mfma_i32_16x16x64_i8 v[114:117], v[172:175], v[204:207], v[114:117]
	v_mfma_i32_16x16x64_i8 v[102:105], v[90:93], v[212:215], v[102:105]
	v_mfma_i32_16x16x64_i8 v[94:97], v[172:175], v[212:215], v[94:97]
	v_mfma_i32_16x16x64_i8 v[78:81], v[90:93], v[220:223], v[78:81]
	v_mfma_i32_16x16x64_i8 v[74:77], v[172:175], v[220:223], v[74:77]
	v_mfma_i32_16x16x64_i8 v[134:137], v[98:101], v[200:203], v[134:137]
	v_mfma_i32_16x16x64_i8 v[130:133], v[176:179], v[200:203], v[130:133]
	v_mfma_i32_16x16x64_i8 v[118:121], v[98:101], v[208:211], v[118:121]
	v_mfma_i32_16x16x64_i8 v[114:117], v[176:179], v[208:211], v[114:117]
	v_mfma_i32_16x16x64_i8 v[102:105], v[98:101], v[216:219], v[102:105]
	v_mfma_i32_16x16x64_i8 v[94:97], v[176:179], v[216:219], v[94:97]
	v_mfma_i32_16x16x64_i8 v[78:81], v[98:101], v[224:227], v[78:81]
	v_mfma_i32_16x16x64_i8 v[74:77], v[176:179], v[224:227], v[74:77]
	v_mfma_i32_16x16x64_i8 v[126:129], v[180:183], v[196:199], v[126:129]
	v_mfma_i32_16x16x64_i8 v[122:125], v[188:191], v[196:199], v[122:125]
	v_mfma_i32_16x16x64_i8 v[110:113], v[180:183], v[204:207], v[110:113]
	v_mfma_i32_16x16x64_i8 v[106:109], v[188:191], v[204:207], v[106:109]
	v_mfma_i32_16x16x64_i8 v[86:89], v[180:183], v[212:215], v[86:89]
	v_mfma_i32_16x16x64_i8 v[82:85], v[188:191], v[212:215], v[82:85]
	v_mfma_i32_16x16x64_i8 v[70:73], v[180:183], v[220:223], v[70:73]
	v_mfma_i32_16x16x64_i8 v[66:69], v[188:191], v[220:223], v[66:69]
	v_mfma_i32_16x16x64_i8 v[126:129], v[184:187], v[200:203], v[126:129]
	v_mfma_i32_16x16x64_i8 v[122:125], v[192:195], v[200:203], v[122:125]
	v_mfma_i32_16x16x64_i8 v[110:113], v[184:187], v[208:211], v[110:113]
	v_mfma_i32_16x16x64_i8 v[106:109], v[192:195], v[208:211], v[106:109]
	v_mfma_i32_16x16x64_i8 v[86:89], v[184:187], v[216:219], v[86:89]
	v_mfma_i32_16x16x64_i8 v[82:85], v[192:195], v[216:219], v[82:85]
	v_mfma_i32_16x16x64_i8 v[70:73], v[184:187], v[224:227], v[70:73]
	v_mfma_i32_16x16x64_i8 v[66:69], v[192:195], v[224:227], v[66:69]
	s_barrier
	s_add_i32 s54, s46, s33
	s_mov_b32 m0, s54
	ds_read_b128 v[196:199], v171 offset:16384
	ds_read_b128 v[200:203], v171 offset:17408
	ds_read_b128 v[204:207], v171 offset:18432
	ds_read_b128 v[208:211], v171 offset:19456
	ds_read_b128 v[212:215], v171 offset:20480
	ds_read_b128 v[216:219], v171 offset:21504
	ds_read_b128 v[220:223], v171 offset:22528
	ds_read_b128 v[224:227], v171 offset:23552
	global_load_lds_dwordx4 v142, s[24:25]
	s_add_i32 m0, s54, 0x2000
	s_add_u32 s54, s24, 0x4000
	s_addc_u32 s55, s25, 0
	s_add_i32 s56, s47, s33
	global_load_lds_dwordx4 v138, s[24:25]
	s_mov_b32 m0, s56
	s_nop 0
	global_load_lds_dwordx4 v142, s[54:55]
	s_add_i32 m0, s56, 0x2000
	s_nop 0
	global_load_lds_dwordx4 v138, s[54:55]
	s_waitcnt vmcnt(6)
	s_waitcnt lgkmcnt(0)
	s_barrier
	s_waitcnt lgkmcnt(0)
	v_mfma_i32_16x16x64_i8 v[62:65], v[90:93], v[196:199], v[62:65]
	v_mfma_i32_16x16x64_i8 v[58:61], v[172:175], v[196:199], v[58:61]
	v_mfma_i32_16x16x64_i8 v[46:49], v[90:93], v[204:207], v[46:49]
	v_mfma_i32_16x16x64_i8 v[42:45], v[172:175], v[204:207], v[42:45]
	v_mfma_i32_16x16x64_i8 v[30:33], v[90:93], v[212:215], v[30:33]
	v_mfma_i32_16x16x64_i8 v[26:29], v[172:175], v[212:215], v[26:29]
	v_mfma_i32_16x16x64_i8 v[14:17], v[90:93], v[220:223], v[14:17]
	v_mfma_i32_16x16x64_i8 v[10:13], v[172:175], v[220:223], v[10:13]
	v_mfma_i32_16x16x64_i8 v[62:65], v[98:101], v[200:203], v[62:65]
	v_mfma_i32_16x16x64_i8 v[58:61], v[176:179], v[200:203], v[58:61]
	v_mfma_i32_16x16x64_i8 v[46:49], v[98:101], v[208:211], v[46:49]
	v_mfma_i32_16x16x64_i8 v[42:45], v[176:179], v[208:211], v[42:45]
	v_mfma_i32_16x16x64_i8 v[30:33], v[98:101], v[216:219], v[30:33]
	v_mfma_i32_16x16x64_i8 v[26:29], v[176:179], v[216:219], v[26:29]
	v_mfma_i32_16x16x64_i8 v[14:17], v[98:101], v[224:227], v[14:17]
	v_mfma_i32_16x16x64_i8 v[10:13], v[176:179], v[224:227], v[10:13]
	v_mfma_i32_16x16x64_i8 v[54:57], v[180:183], v[196:199], v[54:57]
	v_mfma_i32_16x16x64_i8 v[50:53], v[188:191], v[196:199], v[50:53]
	v_mfma_i32_16x16x64_i8 v[38:41], v[180:183], v[204:207], v[38:41]
	v_mfma_i32_16x16x64_i8 v[34:37], v[188:191], v[204:207], v[34:37]
	v_mfma_i32_16x16x64_i8 v[22:25], v[180:183], v[212:215], v[22:25]
	v_mfma_i32_16x16x64_i8 v[18:21], v[188:191], v[212:215], v[18:21]
	v_mfma_i32_16x16x64_i8 v[6:9], v[180:183], v[220:223], v[6:9]
	v_mfma_i32_16x16x64_i8 v[2:5], v[188:191], v[220:223], v[2:5]
	v_mfma_i32_16x16x64_i8 v[54:57], v[184:187], v[200:203], v[54:57]
	v_mfma_i32_16x16x64_i8 v[50:53], v[192:195], v[200:203], v[50:53]
	v_mfma_i32_16x16x64_i8 v[38:41], v[184:187], v[208:211], v[38:41]
	v_mfma_i32_16x16x64_i8 v[34:37], v[192:195], v[208:211], v[34:37]
	v_mfma_i32_16x16x64_i8 v[22:25], v[184:187], v[216:219], v[22:25]
	v_mfma_i32_16x16x64_i8 v[18:21], v[192:195], v[216:219], v[18:21]
	v_mfma_i32_16x16x64_i8 v[6:9], v[184:187], v[224:227], v[6:9]
	v_mfma_i32_16x16x64_i8 v[2:5], v[192:195], v[224:227], v[2:5]
	s_barrier
; #define PG8_STAGE(bufoff, gbase, voff) do { _Pragma("unroll") for (int _i = 0; _i < 2; ++_i) \
;         __builtin_amdgcn_global_load_lds((const unsigned*)((const char*)(gbase) + (voff)[_i]), (LAS unsigned*)(lds + (bufoff) + ldsw + _i * 8192), 16, 0, 0); } while (0)
; #define PG8_LDA(dst, b, h) do { _Pragma("unroll") for (int m = 0; m < 4; ++m) _Pragma("unroll") for (int k = 0; k < 2; ++k) dst[m][k] = *(const LAS bf16x8*)(lds + PG8_SA(b, h) + aoff + m * 2048 + k * 1024); } while (0)
; #define PG8_LDB(dst, b, h) do { _Pragma("unroll") for (int n = 0; n < 2; ++n) _Pragma("unroll") for (int k = 0; k < 2; ++k) dst[n][k] = *(const LAS bf16x8*)(lds + PG8_SB(b, h) + boff + n * 2048 + k * 1024); } while (0)
; #define PG8_WAIT_V(n) asm volatile("s_waitcnt vmcnt(" #n ")" ::: "memory")
; template <class Epi, class Sched, bool I8 = false>
; __device__ __forceinline__ void gemm_phase(LAS unsigned char* lds, const Gemm g, const Sched& S, const Epi& E) {
;     ...
;         for (int t = 0; t < nt; t += 2) {
;             const bool last = (t == nt - 2);
;             const char* a1 = cA + (size_t)(t + 1) * kstep;
;             const char* a2 = last ? nA : cA + (size_t)(t + 2) * kstep; const char* b2 = last ? nB : cB + (size_t)(t + 2) * kstep;
;             const char* a3 = a2 + kstep; const char* b3 = b2 + kstep;
;             PG8_LDB(B0, 0, 0); PG8_LDB(B1, 0, 1); PG8_SCHED; PG8_LDA(At, 0, 0); PG8_STAGE(PG8_SA(1, 1), a1 + hstepA, voffA);
;             PG8_WAIT_V(8); PG8_WAIT_L(0); PG8_BAR; PG8_MMA(0, 0, At, B0); PG8_MMA(0, 1, At, B1); PG8_BAR; PG8_SCHED;
;             PG8_LDA(At, 0, 1); PG8_STAGE(PG8_SB(0, 0), b2, voffB); PG8_STAGE(PG8_SB(0, 1), b2 + hstepB, voffB); PG8_STAGE(PG8_SA(0, 0), a2, voffA);
;             PG8_WAIT_V(8); PG8_WAIT_L(0); PG8_BAR; PG8_MMA(1, 0, At, B0); PG8_MMA(1, 1, At, B1); PG8_BAR; PG8_SCHED;
;             PG8_LDB(B0, 1, 0); PG8_LDB(B1, 1, 1); PG8_SCHED; PG8_LDA(At, 1, 0); PG8_STAGE(PG8_SA(0, 1), a2 + hstepA, voffA);
;             PG8_WAIT_V(8); PG8_WAIT_L(0); PG8_BAR; PG8_MMA(0, 0, At, B0); PG8_MMA(0, 1, At, B1); PG8_BAR; PG8_SCHED;
;             PG8_LDA(At, 1, 1); PG8_STAGE(PG8_SB(1, 0), b3, voffB); PG8_STAGE(PG8_SB(1, 1), b3 + hstepB, voffB); PG8_STAGE(PG8_SA(1, 0), a3, voffA);
;             PG8_WAIT_V(8); PG8_WAIT_L(0); PG8_BAR; PG8_MMA(1, 0, At, B0); PG8_MMA(1, 1, At, B1); PG8_BAR; PG8_SCHED;
;         }
;         if (wr == 0) PG8_BAR;
	s_add_i32 s54, 0, 0x18000
	v_add_u32_e32 v146, s54, v165
	s_add_i32 s55, 0, 0x1c000
	ds_read_b128 v[90:93], v146
	ds_read_b128 v[98:101], v146 offset:1024
	ds_read_b128 v[172:175], v146 offset:2048
	ds_read_b128 v[176:179], v146 offset:3072
	v_add_u32_e32 v146, s55, v165
	ds_read_b128 v[180:183], v146
	ds_read_b128 v[184:187], v146 offset:1024
	ds_read_b128 v[188:191], v146 offset:2048
	ds_read_b128 v[192:195], v146 offset:3072
	s_mov_b32 m0, s36
	s_nop 0
	global_load_lds_dwordx4 v144, s[26:27]
	s_mov_b32 m0, s37
	s_nop 0
	global_load_lds_dwordx4 v140, s[26:27]
	s_add_u32 s26, s26, 0x4000
	s_addc_u32 s27, s27, 0
	s_mov_b32 m0, s38
	ds_read_b128 v[196:199], v171 offset:32768
	ds_read_b128 v[200:203], v171 offset:33792
	ds_read_b128 v[204:207], v171 offset:34816
	ds_read_b128 v[208:211], v171 offset:35840
	ds_read_b128 v[212:215], v171 offset:36864
	ds_read_b128 v[216:219], v171 offset:37888
	ds_read_b128 v[220:223], v171 offset:38912
	ds_read_b128 v[224:227], v171 offset:39936
	global_load_lds_dwordx4 v144, s[26:27]
	s_mov_b32 m0, s39
	s_nop 0
	global_load_lds_dwordx4 v140, s[26:27]
	s_waitcnt vmcnt(8)
	s_waitcnt lgkmcnt(0)
	s_barrier
	s_waitcnt lgkmcnt(0)
	v_mfma_i32_16x16x64_i8 v[134:137], v[90:93], v[196:199], v[134:137]
	v_mfma_i32_16x16x64_i8 v[130:133], v[172:175], v[196:199], v[130:133]
	v_mfma_i32_16x16x64_i8 v[118:121], v[90:93], v[204:207], v[118:121]
	v_mfma_i32_16x16x64_i8 v[114:117], v[172:175], v[204:207], v[114:117]
	v_mfma_i32_16x16x64_i8 v[102:105], v[90:93], v[212:215], v[102:105]
	v_mfma_i32_16x16x64_i8 v[94:97], v[172:175], v[212:215], v[94:97]
	v_mfma_i32_16x16x64_i8 v[78:81], v[90:93], v[220:223], v[78:81]
	v_mfma_i32_16x16x64_i8 v[74:77], v[172:175], v[220:223], v[74:77]
	v_mfma_i32_16x16x64_i8 v[134:137], v[98:101], v[200:203], v[134:137]
	v_mfma_i32_16x16x64_i8 v[130:133], v[176:179], v[200:203], v[130:133]
	v_mfma_i32_16x16x64_i8 v[118:121], v[98:101], v[208:211], v[118:121]
	v_mfma_i32_16x16x64_i8 v[114:117], v[176:179], v[208:211], v[114:117]
	v_mfma_i32_16x16x64_i8 v[102:105], v[98:101], v[216:219], v[102:105]
	v_mfma_i32_16x16x64_i8 v[94:97], v[176:179], v[216:219], v[94:97]
	v_mfma_i32_16x16x64_i8 v[78:81], v[98:101], v[224:227], v[78:81]
	v_mfma_i32_16x16x64_i8 v[74:77], v[176:179], v[224:227], v[74:77]
	v_mfma_i32_16x16x64_i8 v[126:129], v[180:183], v[196:199], v[126:129]
	v_mfma_i32_16x16x64_i8 v[122:125], v[188:191], v[196:199], v[122:125]
	v_mfma_i32_16x16x64_i8 v[110:113], v[180:183], v[204:207], v[110:113]
	v_mfma_i32_16x16x64_i8 v[106:109], v[188:191], v[204:207], v[106:109]
	v_mfma_i32_16x16x64_i8 v[86:89], v[180:183], v[212:215], v[86:89]
	v_mfma_i32_16x16x64_i8 v[82:85], v[188:191], v[212:215], v[82:85]
	v_mfma_i32_16x16x64_i8 v[70:73], v[180:183], v[220:223], v[70:73]
	v_mfma_i32_16x16x64_i8 v[66:69], v[188:191], v[220:223], v[66:69]
	v_mfma_i32_16x16x64_i8 v[126:129], v[184:187], v[200:203], v[126:129]
	v_mfma_i32_16x16x64_i8 v[122:125], v[192:195], v[200:203], v[122:125]
	v_mfma_i32_16x16x64_i8 v[110:113], v[184:187], v[208:211], v[110:113]
	v_mfma_i32_16x16x64_i8 v[106:109], v[192:195], v[208:211], v[106:109]
	v_mfma_i32_16x16x64_i8 v[86:89], v[184:187], v[216:219], v[86:89]
	v_mfma_i32_16x16x64_i8 v[82:85], v[192:195], v[216:219], v[82:85]
	v_mfma_i32_16x16x64_i8 v[70:73], v[184:187], v[224:227], v[70:73]
	v_mfma_i32_16x16x64_i8 v[66:69], v[192:195], v[224:227], v[66:69]
	s_barrier
	s_add_u32 s26, s24, 0x8000
	s_addc_u32 s27, s25, 0
	s_add_i32 s54, s54, s33
	s_mov_b32 m0, s54
	ds_read_b128 v[196:199], v171 offset:49152
	ds_read_b128 v[200:203], v171 offset:50176
	ds_read_b128 v[204:207], v171 offset:51200
	ds_read_b128 v[208:211], v171 offset:52224
	ds_read_b128 v[212:215], v171 offset:53248
	ds_read_b128 v[216:219], v171 offset:54272
	ds_read_b128 v[220:223], v171 offset:55296
	ds_read_b128 v[224:227], v171 offset:56320
	global_load_lds_dwordx4 v142, s[26:27]
	s_add_i32 m0, s54, 0x2000
	s_add_u32 s24, s24, 0xc000
	v_lshl_add_u64 v[158:159], s[26:27], 0, v[138:139]
	s_addc_u32 s25, s25, 0
	s_add_i32 s26, s55, s33
	global_load_lds_dwordx4 v[158:159], off
	s_mov_b32 m0, s26
	s_nop 0
	global_load_lds_dwordx4 v142, s[24:25]
	s_add_i32 m0, s26, 0x2000
	s_nop 0
	global_load_lds_dwordx4 v138, s[24:25]
	s_waitcnt vmcnt(6)
	s_waitcnt lgkmcnt(0)
	s_barrier
	s_waitcnt lgkmcnt(0)
	v_mfma_i32_16x16x64_i8 v[62:65], v[90:93], v[196:199], v[62:65]
	v_mfma_i32_16x16x64_i8 v[58:61], v[172:175], v[196:199], v[58:61]
	v_mfma_i32_16x16x64_i8 v[46:49], v[90:93], v[204:207], v[46:49]
	v_mfma_i32_16x16x64_i8 v[42:45], v[172:175], v[204:207], v[42:45]
	v_mfma_i32_16x16x64_i8 v[30:33], v[90:93], v[212:215], v[30:33]
	v_mfma_i32_16x16x64_i8 v[26:29], v[172:175], v[212:215], v[26:29]
	v_mfma_i32_16x16x64_i8 v[14:17], v[90:93], v[220:223], v[14:17]
	v_mfma_i32_16x16x64_i8 v[10:13], v[172:175], v[220:223], v[10:13]
	v_mfma_i32_16x16x64_i8 v[62:65], v[98:101], v[200:203], v[62:65]
	v_mfma_i32_16x16x64_i8 v[58:61], v[176:179], v[200:203], v[58:61]
	v_mfma_i32_16x16x64_i8 v[46:49], v[98:101], v[208:211], v[46:49]
	v_mfma_i32_16x16x64_i8 v[42:45], v[176:179], v[208:211], v[42:45]
	v_mfma_i32_16x16x64_i8 v[30:33], v[98:101], v[216:219], v[30:33]
	v_mfma_i32_16x16x64_i8 v[26:29], v[176:179], v[216:219], v[26:29]
	v_mfma_i32_16x16x64_i8 v[14:17], v[98:101], v[224:227], v[14:17]
	v_mfma_i32_16x16x64_i8 v[10:13], v[176:179], v[224:227], v[10:13]
	v_mfma_i32_16x16x64_i8 v[54:57], v[180:183], v[196:199], v[54:57]
	v_mfma_i32_16x16x64_i8 v[50:53], v[188:191], v[196:199], v[50:53]
	v_mfma_i32_16x16x64_i8 v[38:41], v[180:183], v[204:207], v[38:41]
	v_mfma_i32_16x16x64_i8 v[34:37], v[188:191], v[204:207], v[34:37]
	v_mfma_i32_16x16x64_i8 v[22:25], v[180:183], v[212:215], v[22:25]
	v_mfma_i32_16x16x64_i8 v[18:21], v[188:191], v[212:215], v[18:21]
	v_mfma_i32_16x16x64_i8 v[6:9], v[180:183], v[220:223], v[6:9]
	v_mfma_i32_16x16x64_i8 v[2:5], v[188:191], v[220:223], v[2:5]
	v_mfma_i32_16x16x64_i8 v[54:57], v[184:187], v[200:203], v[54:57]
	v_mfma_i32_16x16x64_i8 v[50:53], v[192:195], v[200:203], v[50:53]
	v_mfma_i32_16x16x64_i8 v[38:41], v[184:187], v[208:211], v[38:41]
	v_mfma_i32_16x16x64_i8 v[34:37], v[192:195], v[208:211], v[34:37]
	v_mfma_i32_16x16x64_i8 v[22:25], v[184:187], v[216:219], v[22:25]
	v_mfma_i32_16x16x64_i8 v[18:21], v[192:195], v[216:219], v[18:21]
	v_mfma_i32_16x16x64_i8 v[6:9], v[184:187], v[224:227], v[6:9]
	v_mfma_i32_16x16x64_i8 v[2:5], v[192:195], v[224:227], v[2:5]
	s_barrier
	s_add_i32 s53, s53, 2
	s_add_u32 s20, s20, 0x10000
	s_addc_u32 s21, s21, 0
	s_add_u32 s51, s51, 0x10000
	s_addc_u32 s52, s52, 0
	s_cmp_gt_u32 s53, 29
	s_cbranch_scc0 .LBB0_1169
	s_and_b64 vcc, exec, s[8:9]
	s_cbranch_vccz .LBB0_1172
	s_barrier

; #define PG8_STAGE(bufoff, gbase, voff) do { _Pragma("unroll") for (int _i = 0; _i < 2; ++_i) \
;         __builtin_amdgcn_global_load_lds((const unsigned*)((const char*)(gbase) + (voff)[_i]), (LAS unsigned*)(lds + (bufoff) + ldsw + _i * 8192), 16, 0, 0); } while (0)
; #define PG8_LDA(dst, b, h) do { _Pragma("unroll") for (int m = 0; m < 4; ++m) _Pragma("unroll") for (int k = 0; k < 2; ++k) dst[m][k] = *(const LAS bf16x8*)(lds + PG8_SA(b, h) + aoff + m * 2048 + k * 1024); } while (0)
; #define PG8_LDB(dst, b, h) do { _Pragma("unroll") for (int n = 0; n < 2; ++n) _Pragma("unroll") for (int k = 0; k < 2; ++k) dst[n][k] = *(const LAS bf16x8*)(lds + PG8_SB(b, h) + boff + n * 2048 + k * 1024); } while (0)
; #define PG8_WAIT_V(n) asm volatile("s_waitcnt vmcnt(" #n ")" ::: "memory")
; #define PG8_WAIT_L(n) asm volatile("s_waitcnt lgkmcnt(" #n ")" ::: "memory")
; #define PG8_BAR __builtin_amdgcn_s_barrier()
; #define PG8_SCHED __builtin_amdgcn_sched_barrier(0)
; template <class Epi, class Sched, bool I8 = false>
; __device__ __forceinline__ void gemm_phase(LAS unsigned char* lds, const Gemm g, const Sched& S, const Epi& E) {
;     ...
;             const bool last = (t == nt - 2);
;             const char* a1 = cA + (size_t)(t + 1) * kstep;
;             const char* a2 = last ? nA : cA + (size_t)(t + 2) * kstep; const char* b2 = last ? nB : cB + (size_t)(t + 2) * kstep;
;             const char* a3 = a2 + kstep; const char* b3 = b2 + kstep;
;             PG8_LDB(B0, 0, 0); PG8_LDB(B1, 0, 1); PG8_SCHED; PG8_LDA(At, 0, 0); PG8_STAGE(PG8_SA(1, 1), a1 + hstepA, voffA);
;             PG8_WAIT_V(8); PG8_WAIT_L(0); PG8_BAR; PG8_MMA(0, 0, At, B0); PG8_MMA(0, 1, At, B1); PG8_BAR; PG8_SCHED;
;             PG8_LDA(At, 0, 1); PG8_STAGE(PG8_SB(0, 0), b2, voffB); PG8_STAGE(PG8_SB(0, 1), b2 + hstepB, voffB); PG8_STAGE(PG8_SA(0, 0), a2, voffA);
;             PG8_WAIT_V(8); PG8_WAIT_L(0); PG8_BAR; PG8_MMA(1, 0, At, B0); PG8_MMA(1, 1, At, B1); PG8_BAR; PG8_SCHED;
.LBB0_1393:
	ds_read_b128 v[66:69], v180
	ds_read_b128 v[70:73], v180 offset:1024
	ds_read_b128 v[74:77], v180 offset:2048
	ds_read_b128 v[78:81], v180 offset:3072
	ds_read_b128 v[146:149], v181
	ds_read_b128 v[150:153], v181 offset:1024
	ds_read_b128 v[174:177], v181 offset:2048
	ds_read_b128 v[184:187], v181 offset:3072
	s_add_u32 s20, s18, 0x4000
	s_addc_u32 s21, s19, 0
	s_cmpk_eq_i32 s49, 0x52
	s_cselect_b32 s24, s0, s20
	s_cselect_b32 s25, s1, s21
	s_cselect_b32 s22, s16, s47
	s_cselect_b32 s23, s17, s48
	s_add_u32 s20, s24, 0x8000
	s_addc_u32 s21, s25, 0
	s_sub_u32 s98, s18, 0x4000
	s_subb_u32 s99, s19, 0
	s_mov_b32 m0, s37
	s_nop 0
	global_load_lds_dwordx4 v156, s[98:99]
	s_mov_b32 m0, s38
	s_nop 0
	global_load_lds_dwordx4 v160, s[98:99]
	s_add_i32 m0, s31, 0xc000
	ds_read_b128 v[188:191], v182
	ds_read_b128 v[192:195], v182 offset:1024
	ds_read_b128 v[196:199], v182 offset:2048
	ds_read_b128 v[200:203], v182 offset:3072
	ds_read_b128 v[204:207], v182 offset:4096
	ds_read_b128 v[208:211], v182 offset:5120
	ds_read_b128 v[212:215], v182 offset:6144
	ds_read_b128 v[216:219], v182 offset:7168
	global_load_lds_dwordx4 v166, s[18:19]
	s_add_i32 m0, s31, 0xe000
	s_nop 0
	global_load_lds_dwordx4 v168, s[18:19]
	s_waitcnt vmcnt(8)
	s_waitcnt lgkmcnt(0)
	s_barrier
	s_waitcnt lgkmcnt(0)
	v_mfma_i32_16x16x64_i8 v[142:145], v[66:69], v[188:191], v[142:145]
	v_mfma_i32_16x16x64_i8 v[138:141], v[74:77], v[188:191], v[138:141]
	v_mfma_i32_16x16x64_i8 v[126:129], v[66:69], v[196:199], v[126:129]
	v_mfma_i32_16x16x64_i8 v[122:125], v[74:77], v[196:199], v[122:125]
	v_mfma_i32_16x16x64_i8 v[110:113], v[66:69], v[204:207], v[110:113]
	v_mfma_i32_16x16x64_i8 v[106:109], v[74:77], v[204:207], v[106:109]
	v_mfma_i32_16x16x64_i8 v[94:97], v[66:69], v[212:215], v[94:97]
	v_mfma_i32_16x16x64_i8 v[90:93], v[74:77], v[212:215], v[90:93]
	v_mfma_i32_16x16x64_i8 v[142:145], v[70:73], v[192:195], v[142:145]
	v_mfma_i32_16x16x64_i8 v[138:141], v[78:81], v[192:195], v[138:141]
	v_mfma_i32_16x16x64_i8 v[126:129], v[70:73], v[200:203], v[126:129]
	v_mfma_i32_16x16x64_i8 v[122:125], v[78:81], v[200:203], v[122:125]
	v_mfma_i32_16x16x64_i8 v[110:113], v[70:73], v[208:211], v[110:113]
	v_mfma_i32_16x16x64_i8 v[106:109], v[78:81], v[208:211], v[106:109]
	v_mfma_i32_16x16x64_i8 v[94:97], v[70:73], v[216:219], v[94:97]
	v_mfma_i32_16x16x64_i8 v[90:93], v[78:81], v[216:219], v[90:93]
	v_mfma_i32_16x16x64_i8 v[134:137], v[146:149], v[188:191], v[134:137]
	v_mfma_i32_16x16x64_i8 v[130:133], v[174:177], v[188:191], v[130:133]
	v_mfma_i32_16x16x64_i8 v[118:121], v[146:149], v[196:199], v[118:121]
	v_mfma_i32_16x16x64_i8 v[114:117], v[174:177], v[196:199], v[114:117]
	v_mfma_i32_16x16x64_i8 v[102:105], v[146:149], v[204:207], v[102:105]
	v_mfma_i32_16x16x64_i8 v[98:101], v[174:177], v[204:207], v[98:101]
	v_mfma_i32_16x16x64_i8 v[86:89], v[146:149], v[212:215], v[86:89]
	v_mfma_i32_16x16x64_i8 v[82:85], v[174:177], v[212:215], v[82:85]
	v_mfma_i32_16x16x64_i8 v[134:137], v[150:153], v[192:195], v[134:137]
	v_mfma_i32_16x16x64_i8 v[130:133], v[184:187], v[192:195], v[130:133]
	v_mfma_i32_16x16x64_i8 v[118:121], v[150:153], v[200:203], v[118:121]
	v_mfma_i32_16x16x64_i8 v[114:117], v[184:187], v[200:203], v[114:117]
	v_mfma_i32_16x16x64_i8 v[102:105], v[150:153], v[208:211], v[102:105]
	v_mfma_i32_16x16x64_i8 v[98:101], v[184:187], v[208:211], v[98:101]
	v_mfma_i32_16x16x64_i8 v[86:89], v[150:153], v[216:219], v[86:89]
	v_mfma_i32_16x16x64_i8 v[82:85], v[184:187], v[216:219], v[82:85]
	s_barrier
	s_add_i32 s50, s41, s30
	s_mov_b32 m0, s50
	ds_read_b128 v[188:191], v182 offset:16384
	ds_read_b128 v[192:195], v182 offset:17408
	ds_read_b128 v[196:199], v182 offset:18432
	ds_read_b128 v[200:203], v182 offset:19456
	ds_read_b128 v[204:207], v182 offset:20480
	ds_read_b128 v[208:211], v182 offset:21504
	ds_read_b128 v[212:215], v182 offset:22528
	ds_read_b128 v[216:219], v182 offset:23552
	global_load_lds_dwordx4 v158, s[22:23]
	s_add_i32 m0, s50, 0x2000
	s_add_u32 s50, s22, 0x4000
	s_addc_u32 s51, s23, 0
	s_add_i32 s52, s42, s30
	global_load_lds_dwordx4 v162, s[22:23]
	s_mov_b32 m0, s52
	s_nop 0
	global_load_lds_dwordx4 v158, s[50:51]
	s_add_i32 m0, s52, 0x2000
	s_nop 0
	global_load_lds_dwordx4 v162, s[50:51]
	s_waitcnt vmcnt(6)
	s_waitcnt lgkmcnt(0)
	s_barrier
	s_waitcnt lgkmcnt(0)
	v_mfma_i32_16x16x64_i8 v[62:65], v[66:69], v[188:191], v[62:65]
	v_mfma_i32_16x16x64_i8 v[58:61], v[74:77], v[188:191], v[58:61]
	v_mfma_i32_16x16x64_i8 v[46:49], v[66:69], v[196:199], v[46:49]
	v_mfma_i32_16x16x64_i8 v[42:45], v[74:77], v[196:199], v[42:45]
	v_mfma_i32_16x16x64_i8 v[30:33], v[66:69], v[204:207], v[30:33]
	v_mfma_i32_16x16x64_i8 v[26:29], v[74:77], v[204:207], v[26:29]
	v_mfma_i32_16x16x64_i8 v[14:17], v[66:69], v[212:215], v[14:17]
	v_mfma_i32_16x16x64_i8 v[10:13], v[74:77], v[212:215], v[10:13]
	v_mfma_i32_16x16x64_i8 v[62:65], v[70:73], v[192:195], v[62:65]
	v_mfma_i32_16x16x64_i8 v[58:61], v[78:81], v[192:195], v[58:61]
	v_mfma_i32_16x16x64_i8 v[46:49], v[70:73], v[200:203], v[46:49]
	v_mfma_i32_16x16x64_i8 v[42:45], v[78:81], v[200:203], v[42:45]
	v_mfma_i32_16x16x64_i8 v[30:33], v[70:73], v[208:211], v[30:33]
	v_mfma_i32_16x16x64_i8 v[26:29], v[78:81], v[208:211], v[26:29]
	v_mfma_i32_16x16x64_i8 v[14:17], v[70:73], v[216:219], v[14:17]
	v_mfma_i32_16x16x64_i8 v[10:13], v[78:81], v[216:219], v[10:13]
	v_mfma_i32_16x16x64_i8 v[54:57], v[146:149], v[188:191], v[54:57]
	v_mfma_i32_16x16x64_i8 v[50:53], v[174:177], v[188:191], v[50:53]
	v_mfma_i32_16x16x64_i8 v[38:41], v[146:149], v[196:199], v[38:41]
	v_mfma_i32_16x16x64_i8 v[34:37], v[174:177], v[196:199], v[34:37]
	v_mfma_i32_16x16x64_i8 v[22:25], v[146:149], v[204:207], v[22:25]
	v_mfma_i32_16x16x64_i8 v[18:21], v[174:177], v[204:207], v[18:21]
	v_mfma_i32_16x16x64_i8 v[6:9], v[146:149], v[212:215], v[6:9]
	v_mfma_i32_16x16x64_i8 v[2:5], v[174:177], v[212:215], v[2:5]
	v_mfma_i32_16x16x64_i8 v[54:57], v[150:153], v[192:195], v[54:57]
	v_mfma_i32_16x16x64_i8 v[50:53], v[184:187], v[192:195], v[50:53]
	v_mfma_i32_16x16x64_i8 v[38:41], v[150:153], v[200:203], v[38:41]
	v_mfma_i32_16x16x64_i8 v[34:37], v[184:187], v[200:203], v[34:37]
	v_mfma_i32_16x16x64_i8 v[22:25], v[150:153], v[208:211], v[22:25]
	v_mfma_i32_16x16x64_i8 v[18:21], v[184:187], v[208:211], v[18:21]
	v_mfma_i32_16x16x64_i8 v[6:9], v[150:153], v[216:219], v[6:9]
	v_mfma_i32_16x16x64_i8 v[2:5], v[184:187], v[216:219], v[2:5]
	s_barrier
; #define PG8_STAGE(bufoff, gbase, voff) do { _Pragma("unroll") for (int _i = 0; _i < 2; ++_i) \
;         __builtin_amdgcn_global_load_lds((const unsigned*)((const char*)(gbase) + (voff)[_i]), (LAS unsigned*)(lds + (bufoff) + ldsw + _i * 8192), 16, 0, 0); } while (0)
; #define PG8_LDA(dst, b, h) do { _Pragma("unroll") for (int m = 0; m < 4; ++m) _Pragma("unroll") for (int k = 0; k < 2; ++k) dst[m][k] = *(const LAS bf16x8*)(lds + PG8_SA(b, h) + aoff + m * 2048 + k * 1024); } while (0)
; #define PG8_LDB(dst, b, h) do { _Pragma("unroll") for (int n = 0; n < 2; ++n) _Pragma("unroll") for (int k = 0; k < 2; ++k) dst[n][k] = *(const LAS bf16x8*)(lds + PG8_SB(b, h) + boff + n * 2048 + k * 1024); } while (0)
; #define PG8_WAIT_V(n) asm volatile("s_waitcnt vmcnt(" #n ")" ::: "memory")
; template <class Epi, class Sched, bool I8 = false>
; __device__ __forceinline__ void gemm_phase(LAS unsigned char* lds, const Gemm g, const Sched& S, const Epi& E) {
;     ...
;         for (int t = 0; t < nt; t += 2) {
;             const bool last = (t == nt - 2);
;             const char* a1 = cA + (size_t)(t + 1) * kstep;
;             const char* a2 = last ? nA : cA + (size_t)(t + 2) * kstep; const char* b2 = last ? nB : cB + (size_t)(t + 2) * kstep;
;             const char* a3 = a2 + kstep; const char* b3 = b2 + kstep;
;             PG8_LDB(B0, 0, 0); PG8_LDB(B1, 0, 1); PG8_SCHED; PG8_LDA(At, 0, 0); PG8_STAGE(PG8_SA(1, 1), a1 + hstepA, voffA);
;             PG8_WAIT_V(8); PG8_WAIT_L(0); PG8_BAR; PG8_MMA(0, 0, At, B0); PG8_MMA(0, 1, At, B1); PG8_BAR; PG8_SCHED;
;             PG8_LDA(At, 0, 1); PG8_STAGE(PG8_SB(0, 0), b2, voffB); PG8_STAGE(PG8_SB(0, 1), b2 + hstepB, voffB); PG8_STAGE(PG8_SA(0, 0), a2, voffA);
;             PG8_WAIT_V(8); PG8_WAIT_L(0); PG8_BAR; PG8_MMA(1, 0, At, B0); PG8_MMA(1, 1, At, B1); PG8_BAR; PG8_SCHED;
;             PG8_LDB(B0, 1, 0); PG8_LDB(B1, 1, 1); PG8_SCHED; PG8_LDA(At, 1, 0); PG8_STAGE(PG8_SA(0, 1), a2 + hstepA, voffA);
;             PG8_WAIT_V(8); PG8_WAIT_L(0); PG8_BAR; PG8_MMA(0, 0, At, B0); PG8_MMA(0, 1, At, B1); PG8_BAR; PG8_SCHED;
;             PG8_LDA(At, 1, 1); PG8_STAGE(PG8_SB(1, 0), b3, voffB); PG8_STAGE(PG8_SB(1, 1), b3 + hstepB, voffB); PG8_STAGE(PG8_SA(1, 0), a3, voffA);
;             PG8_WAIT_V(8); PG8_WAIT_L(0); PG8_BAR; PG8_MMA(1, 0, At, B0); PG8_MMA(1, 1, At, B1); PG8_BAR; PG8_SCHED;
;         }
;         if (wr == 0) PG8_BAR;
	s_add_i32 s50, 0, 0x18000
	s_add_i32 s51, 0, 0x1c000
	v_add_u32_e32 v78, s50, v178
	v_add_u32_e32 v164, s51, v178
	ds_read_b128 v[66:69], v78
	ds_read_b128 v[70:73], v78 offset:1024
	ds_read_b128 v[74:77], v78 offset:2048
	ds_read_b128 v[78:81], v78 offset:3072
	ds_read_b128 v[146:149], v164
	ds_read_b128 v[150:153], v164 offset:1024
	ds_read_b128 v[174:177], v164 offset:2048
	ds_read_b128 v[184:187], v164 offset:3072
	s_mov_b32 m0, s31
	s_nop 0
	global_load_lds_dwordx4 v156, s[24:25]
	s_mov_b32 m0, s33
	s_nop 0
	global_load_lds_dwordx4 v160, s[24:25]
	s_add_u32 s24, s24, 0x4000
	s_addc_u32 s25, s25, 0
	s_mov_b32 m0, s34
	ds_read_b128 v[188:191], v182 offset:32768
	ds_read_b128 v[192:195], v182 offset:33792
	ds_read_b128 v[196:199], v182 offset:34816
	ds_read_b128 v[200:203], v182 offset:35840
	ds_read_b128 v[204:207], v182 offset:36864
	ds_read_b128 v[208:211], v182 offset:37888
	ds_read_b128 v[212:215], v182 offset:38912
	ds_read_b128 v[216:219], v182 offset:39936
	global_load_lds_dwordx4 v156, s[24:25]
	s_mov_b32 m0, s35
	s_nop 0
	global_load_lds_dwordx4 v160, s[24:25]
	s_waitcnt vmcnt(8)
	s_waitcnt lgkmcnt(0)
	s_barrier
	s_waitcnt lgkmcnt(0)
	v_mfma_i32_16x16x64_i8 v[142:145], v[66:69], v[188:191], v[142:145]
	v_mfma_i32_16x16x64_i8 v[138:141], v[74:77], v[188:191], v[138:141]
	v_mfma_i32_16x16x64_i8 v[126:129], v[66:69], v[196:199], v[126:129]
	v_mfma_i32_16x16x64_i8 v[122:125], v[74:77], v[196:199], v[122:125]
	v_mfma_i32_16x16x64_i8 v[110:113], v[66:69], v[204:207], v[110:113]
	v_mfma_i32_16x16x64_i8 v[106:109], v[74:77], v[204:207], v[106:109]
	v_mfma_i32_16x16x64_i8 v[94:97], v[66:69], v[212:215], v[94:97]
	v_mfma_i32_16x16x64_i8 v[90:93], v[74:77], v[212:215], v[90:93]
	v_mfma_i32_16x16x64_i8 v[142:145], v[70:73], v[192:195], v[142:145]
	v_mfma_i32_16x16x64_i8 v[138:141], v[78:81], v[192:195], v[138:141]
	v_mfma_i32_16x16x64_i8 v[126:129], v[70:73], v[200:203], v[126:129]
	v_mfma_i32_16x16x64_i8 v[122:125], v[78:81], v[200:203], v[122:125]
	v_mfma_i32_16x16x64_i8 v[110:113], v[70:73], v[208:211], v[110:113]
	v_mfma_i32_16x16x64_i8 v[106:109], v[78:81], v[208:211], v[106:109]
	v_mfma_i32_16x16x64_i8 v[94:97], v[70:73], v[216:219], v[94:97]
	v_mfma_i32_16x16x64_i8 v[90:93], v[78:81], v[216:219], v[90:93]
	v_mfma_i32_16x16x64_i8 v[134:137], v[146:149], v[188:191], v[134:137]
	v_mfma_i32_16x16x64_i8 v[130:133], v[174:177], v[188:191], v[130:133]
	v_mfma_i32_16x16x64_i8 v[118:121], v[146:149], v[196:199], v[118:121]
	v_mfma_i32_16x16x64_i8 v[114:117], v[174:177], v[196:199], v[114:117]
	v_mfma_i32_16x16x64_i8 v[102:105], v[146:149], v[204:207], v[102:105]
	v_mfma_i32_16x16x64_i8 v[98:101], v[174:177], v[204:207], v[98:101]
	v_mfma_i32_16x16x64_i8 v[86:89], v[146:149], v[212:215], v[86:89]
	v_mfma_i32_16x16x64_i8 v[82:85], v[174:177], v[212:215], v[82:85]
	v_mfma_i32_16x16x64_i8 v[134:137], v[150:153], v[192:195], v[134:137]
	v_mfma_i32_16x16x64_i8 v[130:133], v[184:187], v[192:195], v[130:133]
	v_mfma_i32_16x16x64_i8 v[118:121], v[150:153], v[200:203], v[118:121]
	v_mfma_i32_16x16x64_i8 v[114:117], v[184:187], v[200:203], v[114:117]
	v_mfma_i32_16x16x64_i8 v[102:105], v[150:153], v[208:211], v[102:105]
	v_mfma_i32_16x16x64_i8 v[98:101], v[184:187], v[208:211], v[98:101]
	v_mfma_i32_16x16x64_i8 v[86:89], v[150:153], v[216:219], v[86:89]
	v_mfma_i32_16x16x64_i8 v[82:85], v[184:187], v[216:219], v[82:85]
	s_barrier
	s_add_u32 s24, s22, 0x8000
	s_addc_u32 s25, s23, 0
	s_add_i32 s50, s50, s30
	s_mov_b32 m0, s50
	ds_read_b128 v[188:191], v182 offset:49152
	ds_read_b128 v[192:195], v182 offset:50176
	ds_read_b128 v[196:199], v182 offset:51200
	ds_read_b128 v[200:203], v182 offset:52224
	ds_read_b128 v[204:207], v182 offset:53248
	ds_read_b128 v[208:211], v182 offset:54272
	ds_read_b128 v[212:215], v182 offset:55296
	ds_read_b128 v[216:219], v182 offset:56320
	global_load_lds_dwordx4 v158, s[24:25]
	s_add_i32 m0, s50, 0x2000
	s_add_u32 s22, s22, 0xc000
	v_lshl_add_u64 v[220:221], s[24:25], 0, v[162:163]
	s_addc_u32 s23, s23, 0
	s_add_i32 s24, s51, s30
	global_load_lds_dwordx4 v[220:221], off
	s_mov_b32 m0, s24
	s_nop 0
	global_load_lds_dwordx4 v158, s[22:23]
	s_add_i32 m0, s24, 0x2000
	s_nop 0
	global_load_lds_dwordx4 v162, s[22:23]
	s_waitcnt vmcnt(6)
	s_waitcnt lgkmcnt(0)
	s_barrier
	s_waitcnt lgkmcnt(0)
	v_mfma_i32_16x16x64_i8 v[62:65], v[66:69], v[188:191], v[62:65]
	v_mfma_i32_16x16x64_i8 v[58:61], v[74:77], v[188:191], v[58:61]
	v_mfma_i32_16x16x64_i8 v[46:49], v[66:69], v[196:199], v[46:49]
	v_mfma_i32_16x16x64_i8 v[42:45], v[74:77], v[196:199], v[42:45]
	v_mfma_i32_16x16x64_i8 v[30:33], v[66:69], v[204:207], v[30:33]
	v_mfma_i32_16x16x64_i8 v[26:29], v[74:77], v[204:207], v[26:29]
	v_mfma_i32_16x16x64_i8 v[14:17], v[66:69], v[212:215], v[14:17]
	v_mfma_i32_16x16x64_i8 v[10:13], v[74:77], v[212:215], v[10:13]
	v_mfma_i32_16x16x64_i8 v[62:65], v[70:73], v[192:195], v[62:65]
	v_mfma_i32_16x16x64_i8 v[58:61], v[78:81], v[192:195], v[58:61]
	v_mfma_i32_16x16x64_i8 v[46:49], v[70:73], v[200:203], v[46:49]
	v_mfma_i32_16x16x64_i8 v[42:45], v[78:81], v[200:203], v[42:45]
	v_mfma_i32_16x16x64_i8 v[30:33], v[70:73], v[208:211], v[30:33]
	v_mfma_i32_16x16x64_i8 v[26:29], v[78:81], v[208:211], v[26:29]
	v_mfma_i32_16x16x64_i8 v[14:17], v[70:73], v[216:219], v[14:17]
	v_mfma_i32_16x16x64_i8 v[10:13], v[78:81], v[216:219], v[10:13]
	v_mfma_i32_16x16x64_i8 v[54:57], v[146:149], v[188:191], v[54:57]
	v_mfma_i32_16x16x64_i8 v[50:53], v[174:177], v[188:191], v[50:53]
	v_mfma_i32_16x16x64_i8 v[38:41], v[146:149], v[196:199], v[38:41]
	v_mfma_i32_16x16x64_i8 v[34:37], v[174:177], v[196:199], v[34:37]
	v_mfma_i32_16x16x64_i8 v[22:25], v[146:149], v[204:207], v[22:25]
	v_mfma_i32_16x16x64_i8 v[18:21], v[174:177], v[204:207], v[18:21]
	v_mfma_i32_16x16x64_i8 v[6:9], v[146:149], v[212:215], v[6:9]
	v_mfma_i32_16x16x64_i8 v[2:5], v[174:177], v[212:215], v[2:5]
	v_mfma_i32_16x16x64_i8 v[54:57], v[150:153], v[192:195], v[54:57]
	v_mfma_i32_16x16x64_i8 v[50:53], v[184:187], v[192:195], v[50:53]
	v_mfma_i32_16x16x64_i8 v[38:41], v[150:153], v[200:203], v[38:41]
	v_mfma_i32_16x16x64_i8 v[34:37], v[184:187], v[200:203], v[34:37]
	v_mfma_i32_16x16x64_i8 v[22:25], v[150:153], v[208:211], v[22:25]
	v_mfma_i32_16x16x64_i8 v[18:21], v[184:187], v[208:211], v[18:21]
	v_mfma_i32_16x16x64_i8 v[6:9], v[150:153], v[216:219], v[6:9]
	v_mfma_i32_16x16x64_i8 v[2:5], v[184:187], v[216:219], v[2:5]
	s_barrier
	s_add_i32 s49, s49, 2
	s_add_u32 s18, s18, 0x10000
	s_addc_u32 s19, s19, 0
	s_add_u32 s47, s47, 0x10000
	s_addc_u32 s48, s48, 0
	s_cmpk_gt_u32 s49, 0x53
	s_cbranch_scc0 .LBB0_1393
	s_and_b64 vcc, exec, s[14:15]
	s_cbranch_vccz .LBB0_1396
	s_barrier

; #define PG8_STAGE(bufoff, gbase, voff) do { _Pragma("unroll") for (int _i = 0; _i < 2; ++_i) \
;         __builtin_amdgcn_global_load_lds((const unsigned*)((const char*)(gbase) + (voff)[_i]), (LAS unsigned*)(lds + (bufoff) + ldsw + _i * 8192), 16, 0, 0); } while (0)
; #define PG8_LDA(dst, b, h) do { _Pragma("unroll") for (int m = 0; m < 4; ++m) _Pragma("unroll") for (int k = 0; k < 2; ++k) dst[m][k] = *(const LAS bf16x8*)(lds + PG8_SA(b, h) + aoff + m * 2048 + k * 1024); } while (0)
; #define PG8_LDB(dst, b, h) do { _Pragma("unroll") for (int n = 0; n < 2; ++n) _Pragma("unroll") for (int k = 0; k < 2; ++k) dst[n][k] = *(const LAS bf16x8*)(lds + PG8_SB(b, h) + boff + n * 2048 + k * 1024); } while (0)
; #define PG8_WAIT_V(n) asm volatile("s_waitcnt vmcnt(" #n ")" ::: "memory")
; #define PG8_WAIT_L(n) asm volatile("s_waitcnt lgkmcnt(" #n ")" ::: "memory")
; #define PG8_BAR __builtin_amdgcn_s_barrier()
; #define PG8_SCHED __builtin_amdgcn_sched_barrier(0)
; template <class Epi, class Sched, bool I8 = false>
; __device__ __forceinline__ void gemm_phase(LAS unsigned char* lds, const Gemm g, const Sched& S, const Epi& E) {
;     ...
;             const bool last = (t == nt - 2);
;             const char* a1 = cA + (size_t)(t + 1) * kstep;
;             const char* a2 = last ? nA : cA + (size_t)(t + 2) * kstep; const char* b2 = last ? nB : cB + (size_t)(t + 2) * kstep;
;             const char* a3 = a2 + kstep; const char* b3 = b2 + kstep;
;             PG8_LDB(B0, 0, 0); PG8_LDB(B1, 0, 1); PG8_SCHED; PG8_LDA(At, 0, 0); PG8_STAGE(PG8_SA(1, 1), a1 + hstepA, voffA);
;             PG8_WAIT_V(8); PG8_WAIT_L(0); PG8_BAR; PG8_MMA(0, 0, At, B0); PG8_MMA(0, 1, At, B1); PG8_BAR; PG8_SCHED;
;             PG8_LDA(At, 0, 1); PG8_STAGE(PG8_SB(0, 0), b2, voffB); PG8_STAGE(PG8_SB(0, 1), b2 + hstepB, voffB); PG8_STAGE(PG8_SA(0, 0), a2, voffA);
;             PG8_WAIT_V(8); PG8_WAIT_L(0); PG8_BAR; PG8_MMA(1, 0, At, B0); PG8_MMA(1, 1, At, B1); PG8_BAR; PG8_SCHED;
.LBB0_1482:
	ds_read_b128 v[152:155], v182
	ds_read_b128 v[156:159], v182 offset:1024
	ds_read_b128 v[160:163], v182 offset:2048
	ds_read_b128 v[164:167], v182 offset:3072
	ds_read_b128 v[168:171], v183
	ds_read_b128 v[172:175], v183 offset:1024
	ds_read_b128 v[176:179], v183 offset:2048
	ds_read_b128 v[186:189], v183 offset:3072
	s_add_u32 s38, s8, 0x4000
	s_addc_u32 s39, s9, 0
	s_cmp_eq_u32 s47, 60
	s_cselect_b32 s42, s31, s38
	s_cselect_b32 s43, s7, s39
	s_cselect_b32 s40, s44, s45
	s_cselect_b32 s41, s29, s46
	s_add_u32 s38, s42, 0x8000
	s_addc_u32 s39, s43, 0
	s_sub_u32 s98, s8, 0x4000
	s_subb_u32 s99, s9, 0
	s_mov_b32 m0, s58
	s_nop 0
	global_load_lds_dwordx4 v130, s[98:99]
	s_mov_b32 m0, s59
	s_nop 0
	global_load_lds_dwordx4 v134, s[98:99]
	s_add_i32 m0, s33, 0xc000
	ds_read_b128 v[190:193], v184
	ds_read_b128 v[194:197], v184 offset:1024
	ds_read_b128 v[198:201], v184 offset:2048
	ds_read_b128 v[202:205], v184 offset:3072
	ds_read_b128 v[206:209], v184 offset:4096
	ds_read_b128 v[210:213], v184 offset:5120
	ds_read_b128 v[214:217], v184 offset:6144
	ds_read_b128 v[218:221], v184 offset:7168
	global_load_lds_dwordx4 v144, s[8:9]
	s_add_i32 m0, s33, 0xe000
	s_nop 0
	global_load_lds_dwordx4 v146, s[8:9]
	s_waitcnt vmcnt(8)
	s_waitcnt lgkmcnt(0)
	s_barrier
	s_waitcnt lgkmcnt(0)
	v_mfma_f32_16x16x32_bf16 v[126:129], v[152:155], v[190:193], v[126:129]
	v_mfma_f32_16x16x32_bf16 v[122:125], v[160:163], v[190:193], v[122:125]
	v_mfma_f32_16x16x32_bf16 v[110:113], v[152:155], v[198:201], v[110:113]
	v_mfma_f32_16x16x32_bf16 v[106:109], v[160:163], v[198:201], v[106:109]
	v_mfma_f32_16x16x32_bf16 v[94:97], v[152:155], v[206:209], v[94:97]
	v_mfma_f32_16x16x32_bf16 v[90:93], v[160:163], v[206:209], v[90:93]
	v_mfma_f32_16x16x32_bf16 v[78:81], v[152:155], v[214:217], v[78:81]
	v_mfma_f32_16x16x32_bf16 v[74:77], v[160:163], v[214:217], v[74:77]
	v_mfma_f32_16x16x32_bf16 v[126:129], v[156:159], v[194:197], v[126:129]
	v_mfma_f32_16x16x32_bf16 v[122:125], v[164:167], v[194:197], v[122:125]
	v_mfma_f32_16x16x32_bf16 v[110:113], v[156:159], v[202:205], v[110:113]
	v_mfma_f32_16x16x32_bf16 v[106:109], v[164:167], v[202:205], v[106:109]
	v_mfma_f32_16x16x32_bf16 v[94:97], v[156:159], v[210:213], v[94:97]
	v_mfma_f32_16x16x32_bf16 v[90:93], v[164:167], v[210:213], v[90:93]
	v_mfma_f32_16x16x32_bf16 v[78:81], v[156:159], v[218:221], v[78:81]
	v_mfma_f32_16x16x32_bf16 v[74:77], v[164:167], v[218:221], v[74:77]
	v_mfma_f32_16x16x32_bf16 v[118:121], v[168:171], v[190:193], v[118:121]
	v_mfma_f32_16x16x32_bf16 v[114:117], v[176:179], v[190:193], v[114:117]
	v_mfma_f32_16x16x32_bf16 v[102:105], v[168:171], v[198:201], v[102:105]
	v_mfma_f32_16x16x32_bf16 v[98:101], v[176:179], v[198:201], v[98:101]
	v_mfma_f32_16x16x32_bf16 v[86:89], v[168:171], v[206:209], v[86:89]
	v_mfma_f32_16x16x32_bf16 v[82:85], v[176:179], v[206:209], v[82:85]
	v_mfma_f32_16x16x32_bf16 v[70:73], v[168:171], v[214:217], v[70:73]
	v_mfma_f32_16x16x32_bf16 v[66:69], v[176:179], v[214:217], v[66:69]
	v_mfma_f32_16x16x32_bf16 v[118:121], v[172:175], v[194:197], v[118:121]
	v_mfma_f32_16x16x32_bf16 v[114:117], v[186:189], v[194:197], v[114:117]
	v_mfma_f32_16x16x32_bf16 v[102:105], v[172:175], v[202:205], v[102:105]
	v_mfma_f32_16x16x32_bf16 v[98:101], v[186:189], v[202:205], v[98:101]
	v_mfma_f32_16x16x32_bf16 v[86:89], v[172:175], v[210:213], v[86:89]
	v_mfma_f32_16x16x32_bf16 v[82:85], v[186:189], v[210:213], v[82:85]
	v_mfma_f32_16x16x32_bf16 v[70:73], v[172:175], v[218:221], v[70:73]
	v_mfma_f32_16x16x32_bf16 v[66:69], v[186:189], v[218:221], v[66:69]
	s_barrier
	s_add_i32 s48, s63, s25
	s_mov_b32 m0, s48
	ds_read_b128 v[190:193], v184 offset:16384
	ds_read_b128 v[194:197], v184 offset:17408
	ds_read_b128 v[198:201], v184 offset:18432
	ds_read_b128 v[202:205], v184 offset:19456
	ds_read_b128 v[206:209], v184 offset:20480
	ds_read_b128 v[210:213], v184 offset:21504
	ds_read_b128 v[214:217], v184 offset:22528
	ds_read_b128 v[218:221], v184 offset:23552
	global_load_lds_dwordx4 v132, s[40:41]
	s_add_i32 m0, s48, 0x2000
	s_add_u32 s48, s40, 0x4000
	s_addc_u32 s49, s41, 0
	s_add_i32 s50, s64, s25
	global_load_lds_dwordx4 v136, s[40:41]
	s_mov_b32 m0, s50
	s_nop 0
	global_load_lds_dwordx4 v132, s[48:49]
	s_add_i32 m0, s50, 0x2000
	s_nop 0
	global_load_lds_dwordx4 v136, s[48:49]
	s_waitcnt vmcnt(6)
	s_waitcnt lgkmcnt(0)
	s_barrier
	s_waitcnt lgkmcnt(0)
	v_mfma_f32_16x16x32_bf16 v[62:65], v[152:155], v[190:193], v[62:65]
	v_mfma_f32_16x16x32_bf16 v[58:61], v[160:163], v[190:193], v[58:61]
	v_mfma_f32_16x16x32_bf16 v[46:49], v[152:155], v[198:201], v[46:49]
	v_mfma_f32_16x16x32_bf16 v[42:45], v[160:163], v[198:201], v[42:45]
	v_mfma_f32_16x16x32_bf16 v[30:33], v[152:155], v[206:209], v[30:33]
	v_mfma_f32_16x16x32_bf16 v[26:29], v[160:163], v[206:209], v[26:29]
	v_mfma_f32_16x16x32_bf16 v[14:17], v[152:155], v[214:217], v[14:17]
	v_mfma_f32_16x16x32_bf16 v[10:13], v[160:163], v[214:217], v[10:13]
	v_mfma_f32_16x16x32_bf16 v[62:65], v[156:159], v[194:197], v[62:65]
	v_mfma_f32_16x16x32_bf16 v[58:61], v[164:167], v[194:197], v[58:61]
	v_mfma_f32_16x16x32_bf16 v[46:49], v[156:159], v[202:205], v[46:49]
	v_mfma_f32_16x16x32_bf16 v[42:45], v[164:167], v[202:205], v[42:45]
	v_mfma_f32_16x16x32_bf16 v[30:33], v[156:159], v[210:213], v[30:33]
	v_mfma_f32_16x16x32_bf16 v[26:29], v[164:167], v[210:213], v[26:29]
	v_mfma_f32_16x16x32_bf16 v[14:17], v[156:159], v[218:221], v[14:17]
	v_mfma_f32_16x16x32_bf16 v[10:13], v[164:167], v[218:221], v[10:13]
	v_mfma_f32_16x16x32_bf16 v[54:57], v[168:171], v[190:193], v[54:57]
	v_mfma_f32_16x16x32_bf16 v[50:53], v[176:179], v[190:193], v[50:53]
	v_mfma_f32_16x16x32_bf16 v[38:41], v[168:171], v[198:201], v[38:41]
	v_mfma_f32_16x16x32_bf16 v[34:37], v[176:179], v[198:201], v[34:37]
	v_mfma_f32_16x16x32_bf16 v[22:25], v[168:171], v[206:209], v[22:25]
	v_mfma_f32_16x16x32_bf16 v[18:21], v[176:179], v[206:209], v[18:21]
	v_mfma_f32_16x16x32_bf16 v[6:9], v[168:171], v[214:217], v[6:9]
	v_mfma_f32_16x16x32_bf16 v[2:5], v[176:179], v[214:217], v[2:5]
	v_mfma_f32_16x16x32_bf16 v[54:57], v[172:175], v[194:197], v[54:57]
	v_mfma_f32_16x16x32_bf16 v[50:53], v[186:189], v[194:197], v[50:53]
	v_mfma_f32_16x16x32_bf16 v[38:41], v[172:175], v[202:205], v[38:41]
	v_mfma_f32_16x16x32_bf16 v[34:37], v[186:189], v[202:205], v[34:37]
	v_mfma_f32_16x16x32_bf16 v[22:25], v[172:175], v[210:213], v[22:25]
	v_mfma_f32_16x16x32_bf16 v[18:21], v[186:189], v[210:213], v[18:21]
	v_mfma_f32_16x16x32_bf16 v[6:9], v[172:175], v[218:221], v[6:9]
	v_mfma_f32_16x16x32_bf16 v[2:5], v[186:189], v[218:221], v[2:5]
	s_barrier
; #define PG8_STAGE(bufoff, gbase, voff) do { _Pragma("unroll") for (int _i = 0; _i < 2; ++_i) \
;         __builtin_amdgcn_global_load_lds((const unsigned*)((const char*)(gbase) + (voff)[_i]), (LAS unsigned*)(lds + (bufoff) + ldsw + _i * 8192), 16, 0, 0); } while (0)
; #define PG8_LDA(dst, b, h) do { _Pragma("unroll") for (int m = 0; m < 4; ++m) _Pragma("unroll") for (int k = 0; k < 2; ++k) dst[m][k] = *(const LAS bf16x8*)(lds + PG8_SA(b, h) + aoff + m * 2048 + k * 1024); } while (0)
; #define PG8_LDB(dst, b, h) do { _Pragma("unroll") for (int n = 0; n < 2; ++n) _Pragma("unroll") for (int k = 0; k < 2; ++k) dst[n][k] = *(const LAS bf16x8*)(lds + PG8_SB(b, h) + boff + n * 2048 + k * 1024); } while (0)
; #define PG8_WAIT_V(n) asm volatile("s_waitcnt vmcnt(" #n ")" ::: "memory")
; template <class Epi, class Sched, bool I8 = false>
; __device__ __forceinline__ void gemm_phase(LAS unsigned char* lds, const Gemm g, const Sched& S, const Epi& E) {
;     ...
;         for (int t = 0; t < nt; t += 2) {
;             const bool last = (t == nt - 2);
;             const char* a1 = cA + (size_t)(t + 1) * kstep;
;             const char* a2 = last ? nA : cA + (size_t)(t + 2) * kstep; const char* b2 = last ? nB : cB + (size_t)(t + 2) * kstep;
;             const char* a3 = a2 + kstep; const char* b3 = b2 + kstep;
;             PG8_LDB(B0, 0, 0); PG8_LDB(B1, 0, 1); PG8_SCHED; PG8_LDA(At, 0, 0); PG8_STAGE(PG8_SA(1, 1), a1 + hstepA, voffA);
;             PG8_WAIT_V(8); PG8_WAIT_L(0); PG8_BAR; PG8_MMA(0, 0, At, B0); PG8_MMA(0, 1, At, B1); PG8_BAR; PG8_SCHED;
;             PG8_LDA(At, 0, 1); PG8_STAGE(PG8_SB(0, 0), b2, voffB); PG8_STAGE(PG8_SB(0, 1), b2 + hstepB, voffB); PG8_STAGE(PG8_SA(0, 0), a2, voffA);
;             PG8_WAIT_V(8); PG8_WAIT_L(0); PG8_BAR; PG8_MMA(1, 0, At, B0); PG8_MMA(1, 1, At, B1); PG8_BAR; PG8_SCHED;
;             PG8_LDB(B0, 1, 0); PG8_LDB(B1, 1, 1); PG8_SCHED; PG8_LDA(At, 1, 0); PG8_STAGE(PG8_SA(0, 1), a2 + hstepA, voffA);
;             PG8_WAIT_V(8); PG8_WAIT_L(0); PG8_BAR; PG8_MMA(0, 0, At, B0); PG8_MMA(0, 1, At, B1); PG8_BAR; PG8_SCHED;
;             PG8_LDA(At, 1, 1); PG8_STAGE(PG8_SB(1, 0), b3, voffB); PG8_STAGE(PG8_SB(1, 1), b3 + hstepB, voffB); PG8_STAGE(PG8_SA(1, 0), a3, voffA);
;             PG8_WAIT_V(8); PG8_WAIT_L(0); PG8_BAR; PG8_MMA(1, 0, At, B0); PG8_MMA(1, 1, At, B1); PG8_BAR; PG8_SCHED;
;         }
;         if (wr == 0) PG8_BAR;
	s_add_i32 s48, 0, 0x18000
	v_add_u32_e32 v138, s48, v181
	s_add_i32 s49, 0, 0x1c000
	ds_read_b128 v[152:155], v138
	ds_read_b128 v[156:159], v138 offset:1024
	ds_read_b128 v[160:163], v138 offset:2048
	ds_read_b128 v[164:167], v138 offset:3072
	v_add_u32_e32 v138, s49, v181
	ds_read_b128 v[168:171], v138
	ds_read_b128 v[172:175], v138 offset:1024
	ds_read_b128 v[176:179], v138 offset:2048
	ds_read_b128 v[186:189], v138 offset:3072
	s_mov_b32 m0, s33
	s_nop 0
	global_load_lds_dwordx4 v130, s[42:43]
	s_mov_b32 m0, s52
	s_nop 0
	global_load_lds_dwordx4 v134, s[42:43]
	s_add_u32 s42, s42, 0x4000
	s_addc_u32 s43, s43, 0
	s_mov_b32 m0, s53
	ds_read_b128 v[190:193], v184 offset:32768
	ds_read_b128 v[194:197], v184 offset:33792
	ds_read_b128 v[198:201], v184 offset:34816
	ds_read_b128 v[202:205], v184 offset:35840
	ds_read_b128 v[206:209], v184 offset:36864
	ds_read_b128 v[210:213], v184 offset:37888
	ds_read_b128 v[214:217], v184 offset:38912
	ds_read_b128 v[218:221], v184 offset:39936
	global_load_lds_dwordx4 v130, s[42:43]
	s_mov_b32 m0, s54
	s_nop 0
	global_load_lds_dwordx4 v134, s[42:43]
	s_waitcnt vmcnt(8)
	s_waitcnt lgkmcnt(0)
	s_barrier
	s_waitcnt lgkmcnt(0)
	v_mfma_f32_16x16x32_bf16 v[126:129], v[152:155], v[190:193], v[126:129]
	v_mfma_f32_16x16x32_bf16 v[122:125], v[160:163], v[190:193], v[122:125]
	v_mfma_f32_16x16x32_bf16 v[110:113], v[152:155], v[198:201], v[110:113]
	v_mfma_f32_16x16x32_bf16 v[106:109], v[160:163], v[198:201], v[106:109]
	v_mfma_f32_16x16x32_bf16 v[94:97], v[152:155], v[206:209], v[94:97]
	v_mfma_f32_16x16x32_bf16 v[90:93], v[160:163], v[206:209], v[90:93]
	v_mfma_f32_16x16x32_bf16 v[78:81], v[152:155], v[214:217], v[78:81]
	v_mfma_f32_16x16x32_bf16 v[74:77], v[160:163], v[214:217], v[74:77]
	v_mfma_f32_16x16x32_bf16 v[126:129], v[156:159], v[194:197], v[126:129]
	v_mfma_f32_16x16x32_bf16 v[122:125], v[164:167], v[194:197], v[122:125]
	v_mfma_f32_16x16x32_bf16 v[110:113], v[156:159], v[202:205], v[110:113]
	v_mfma_f32_16x16x32_bf16 v[106:109], v[164:167], v[202:205], v[106:109]
	v_mfma_f32_16x16x32_bf16 v[94:97], v[156:159], v[210:213], v[94:97]
	v_mfma_f32_16x16x32_bf16 v[90:93], v[164:167], v[210:213], v[90:93]
	v_mfma_f32_16x16x32_bf16 v[78:81], v[156:159], v[218:221], v[78:81]
	v_mfma_f32_16x16x32_bf16 v[74:77], v[164:167], v[218:221], v[74:77]
	v_mfma_f32_16x16x32_bf16 v[118:121], v[168:171], v[190:193], v[118:121]
	v_mfma_f32_16x16x32_bf16 v[114:117], v[176:179], v[190:193], v[114:117]
	v_mfma_f32_16x16x32_bf16 v[102:105], v[168:171], v[198:201], v[102:105]
	v_mfma_f32_16x16x32_bf16 v[98:101], v[176:179], v[198:201], v[98:101]
	v_mfma_f32_16x16x32_bf16 v[86:89], v[168:171], v[206:209], v[86:89]
	v_mfma_f32_16x16x32_bf16 v[82:85], v[176:179], v[206:209], v[82:85]
	v_mfma_f32_16x16x32_bf16 v[70:73], v[168:171], v[214:217], v[70:73]
	v_mfma_f32_16x16x32_bf16 v[66:69], v[176:179], v[214:217], v[66:69]
	v_mfma_f32_16x16x32_bf16 v[118:121], v[172:175], v[194:197], v[118:121]
	v_mfma_f32_16x16x32_bf16 v[114:117], v[186:189], v[194:197], v[114:117]
	v_mfma_f32_16x16x32_bf16 v[102:105], v[172:175], v[202:205], v[102:105]
	v_mfma_f32_16x16x32_bf16 v[98:101], v[186:189], v[202:205], v[98:101]
	v_mfma_f32_16x16x32_bf16 v[86:89], v[172:175], v[210:213], v[86:89]
	v_mfma_f32_16x16x32_bf16 v[82:85], v[186:189], v[210:213], v[82:85]
	v_mfma_f32_16x16x32_bf16 v[70:73], v[172:175], v[218:221], v[70:73]
	v_mfma_f32_16x16x32_bf16 v[66:69], v[186:189], v[218:221], v[66:69]
	s_barrier
	s_add_u32 s42, s40, 0x8000
	s_addc_u32 s43, s41, 0
	s_add_i32 s48, s48, s25
	s_mov_b32 m0, s48
	ds_read_b128 v[190:193], v184 offset:49152
	ds_read_b128 v[194:197], v184 offset:50176
	ds_read_b128 v[198:201], v184 offset:51200
	ds_read_b128 v[202:205], v184 offset:52224
	ds_read_b128 v[206:209], v184 offset:53248
	ds_read_b128 v[210:213], v184 offset:54272
	ds_read_b128 v[214:217], v184 offset:55296
	ds_read_b128 v[218:221], v184 offset:56320
	global_load_lds_dwordx4 v132, s[42:43]
	s_add_i32 m0, s48, 0x2000
	s_add_u32 s40, s40, 0xc000
	v_lshl_add_u64 v[222:223], s[42:43], 0, v[136:137]
	s_addc_u32 s41, s41, 0
	s_add_i32 s42, s49, s25
	global_load_lds_dwordx4 v[222:223], off
	s_mov_b32 m0, s42
	s_nop 0
	global_load_lds_dwordx4 v132, s[40:41]
	s_add_i32 m0, s42, 0x2000
	s_nop 0
	global_load_lds_dwordx4 v136, s[40:41]
	s_waitcnt vmcnt(6)
	s_waitcnt lgkmcnt(0)
	s_barrier
	s_waitcnt lgkmcnt(0)
	v_mfma_f32_16x16x32_bf16 v[62:65], v[152:155], v[190:193], v[62:65]
	v_mfma_f32_16x16x32_bf16 v[58:61], v[160:163], v[190:193], v[58:61]
	v_mfma_f32_16x16x32_bf16 v[46:49], v[152:155], v[198:201], v[46:49]
	v_mfma_f32_16x16x32_bf16 v[42:45], v[160:163], v[198:201], v[42:45]
	v_mfma_f32_16x16x32_bf16 v[30:33], v[152:155], v[206:209], v[30:33]
	v_mfma_f32_16x16x32_bf16 v[26:29], v[160:163], v[206:209], v[26:29]
	v_mfma_f32_16x16x32_bf16 v[14:17], v[152:155], v[214:217], v[14:17]
	v_mfma_f32_16x16x32_bf16 v[10:13], v[160:163], v[214:217], v[10:13]
	v_mfma_f32_16x16x32_bf16 v[62:65], v[156:159], v[194:197], v[62:65]
	v_mfma_f32_16x16x32_bf16 v[58:61], v[164:167], v[194:197], v[58:61]
	v_mfma_f32_16x16x32_bf16 v[46:49], v[156:159], v[202:205], v[46:49]
	v_mfma_f32_16x16x32_bf16 v[42:45], v[164:167], v[202:205], v[42:45]
	v_mfma_f32_16x16x32_bf16 v[30:33], v[156:159], v[210:213], v[30:33]
	v_mfma_f32_16x16x32_bf16 v[26:29], v[164:167], v[210:213], v[26:29]
	v_mfma_f32_16x16x32_bf16 v[14:17], v[156:159], v[218:221], v[14:17]
	v_mfma_f32_16x16x32_bf16 v[10:13], v[164:167], v[218:221], v[10:13]
	v_mfma_f32_16x16x32_bf16 v[54:57], v[168:171], v[190:193], v[54:57]
	v_mfma_f32_16x16x32_bf16 v[50:53], v[176:179], v[190:193], v[50:53]
	v_mfma_f32_16x16x32_bf16 v[38:41], v[168:171], v[198:201], v[38:41]
	v_mfma_f32_16x16x32_bf16 v[34:37], v[176:179], v[198:201], v[34:37]
	v_mfma_f32_16x16x32_bf16 v[22:25], v[168:171], v[206:209], v[22:25]
	v_mfma_f32_16x16x32_bf16 v[18:21], v[176:179], v[206:209], v[18:21]
	v_mfma_f32_16x16x32_bf16 v[6:9], v[168:171], v[214:217], v[6:9]
	v_mfma_f32_16x16x32_bf16 v[2:5], v[176:179], v[214:217], v[2:5]
	v_mfma_f32_16x16x32_bf16 v[54:57], v[172:175], v[194:197], v[54:57]
	v_mfma_f32_16x16x32_bf16 v[50:53], v[186:189], v[194:197], v[50:53]
	v_mfma_f32_16x16x32_bf16 v[38:41], v[172:175], v[202:205], v[38:41]
	v_mfma_f32_16x16x32_bf16 v[34:37], v[186:189], v[202:205], v[34:37]
	v_mfma_f32_16x16x32_bf16 v[22:25], v[172:175], v[210:213], v[22:25]
	v_mfma_f32_16x16x32_bf16 v[18:21], v[186:189], v[210:213], v[18:21]
	v_mfma_f32_16x16x32_bf16 v[6:9], v[172:175], v[218:221], v[6:9]
	v_mfma_f32_16x16x32_bf16 v[2:5], v[186:189], v[218:221], v[2:5]
	s_barrier
	s_add_i32 s47, s47, 2
	s_add_u32 s8, s8, 0x10000
	s_addc_u32 s9, s9, 0
	s_add_u32 s45, s45, 0x10000
	s_addc_u32 s46, s46, 0
	s_cmp_gt_u32 s47, 61
	s_cbranch_scc0 .LBB0_1482
	s_and_b64 vcc, exec, s[20:21]
	s_cbranch_vccz .LBB0_1485
	s_barrier

; #define PG8_STAGE(bufoff, gbase, voff) do { _Pragma("unroll") for (int _i = 0; _i < 2; ++_i) \
;         __builtin_amdgcn_global_load_lds((const unsigned*)((const char*)(gbase) + (voff)[_i]), (LAS unsigned*)(lds + (bufoff) + ldsw + _i * 8192), 16, 0, 0); } while (0)
; #define PG8_LDA(dst, b, h) do { _Pragma("unroll") for (int m = 0; m < 4; ++m) _Pragma("unroll") for (int k = 0; k < 2; ++k) dst[m][k] = *(const LAS bf16x8*)(lds + PG8_SA(b, h) + aoff + m * 2048 + k * 1024); } while (0)
; #define PG8_LDB(dst, b, h) do { _Pragma("unroll") for (int n = 0; n < 2; ++n) _Pragma("unroll") for (int k = 0; k < 2; ++k) dst[n][k] = *(const LAS bf16x8*)(lds + PG8_SB(b, h) + boff + n * 2048 + k * 1024); } while (0)
; #define PG8_WAIT_V(n) asm volatile("s_waitcnt vmcnt(" #n ")" ::: "memory")
; #define PG8_WAIT_L(n) asm volatile("s_waitcnt lgkmcnt(" #n ")" ::: "memory")
; #define PG8_BAR __builtin_amdgcn_s_barrier()
; #define PG8_SCHED __builtin_amdgcn_sched_barrier(0)
; template <class Epi, class Sched, bool I8 = false>
; __device__ __forceinline__ void gemm_phase(LAS unsigned char* lds, const Gemm g, const Sched& S, const Epi& E) {
;     ...
;             const bool last = (t == nt - 2);
;             const char* a1 = cA + (size_t)(t + 1) * kstep;
;             const char* a2 = last ? nA : cA + (size_t)(t + 2) * kstep; const char* b2 = last ? nB : cB + (size_t)(t + 2) * kstep;
;             const char* a3 = a2 + kstep; const char* b3 = b2 + kstep;
;             PG8_LDB(B0, 0, 0); PG8_LDB(B1, 0, 1); PG8_SCHED; PG8_LDA(At, 0, 0); PG8_STAGE(PG8_SA(1, 1), a1 + hstepA, voffA);
;             PG8_WAIT_V(8); PG8_WAIT_L(0); PG8_BAR; PG8_MMA(0, 0, At, B0); PG8_MMA(0, 1, At, B1); PG8_BAR; PG8_SCHED;
;             PG8_LDA(At, 0, 1); PG8_STAGE(PG8_SB(0, 0), b2, voffB); PG8_STAGE(PG8_SB(0, 1), b2 + hstepB, voffB); PG8_STAGE(PG8_SA(0, 0), a2, voffA);
;             PG8_WAIT_V(8); PG8_WAIT_L(0); PG8_BAR; PG8_MMA(1, 0, At, B0); PG8_MMA(1, 1, At, B1); PG8_BAR; PG8_SCHED;
.LBB0_2685:
	ds_read_b128 v[130:133], v166
	ds_read_b128 v[134:137], v166 offset:1024
	ds_read_b128 v[158:161], v166 offset:2048
	ds_read_b128 v[170:173], v166 offset:3072
	ds_read_b128 v[174:177], v167
	ds_read_b128 v[178:181], v167 offset:1024
	ds_read_b128 v[182:185], v167 offset:2048
	ds_read_b128 v[186:189], v167 offset:3072
	s_add_u32 s12, s10, 0x4000
	s_addc_u32 s13, s11, 0
	s_cmp_eq_u32 s45, 4
	s_cselect_b32 s16, s40, s12
	s_cselect_b32 s17, s39, s13
	s_cselect_b32 s14, s42, s43
	s_cselect_b32 s15, s41, s44
	s_add_u32 s12, s16, 0x8000
	s_addc_u32 s13, s17, 0
	s_sub_u32 s98, s10, 0x4000
	s_subb_u32 s99, s11, 0
	s_mov_b32 m0, s33
	s_nop 0
	global_load_lds_dwordx4 v144, s[98:99]
	s_mov_b32 m0, s34
	s_nop 0
	global_load_lds_dwordx4 v140, s[98:99]
	s_add_i32 m0, s26, 0xc000
	ds_read_b128 v[190:193], v168
	ds_read_b128 v[194:197], v168 offset:1024
	ds_read_b128 v[198:201], v168 offset:2048
	ds_read_b128 v[202:205], v168 offset:3072
	ds_read_b128 v[206:209], v168 offset:4096
	ds_read_b128 v[210:213], v168 offset:5120
	ds_read_b128 v[214:217], v168 offset:6144
	ds_read_b128 v[218:221], v168 offset:7168
	global_load_lds_dwordx4 v150, s[10:11]
	s_add_i32 m0, s26, 0xe000
	s_nop 0
	global_load_lds_dwordx4 v152, s[10:11]
	s_waitcnt vmcnt(8)
	s_waitcnt lgkmcnt(0)
	s_barrier
	s_waitcnt lgkmcnt(0)
	v_mfma_f32_16x16x32_bf16 v[126:129], v[130:133], v[190:193], v[126:129]
	v_mfma_f32_16x16x32_bf16 v[122:125], v[158:161], v[190:193], v[122:125]
	v_mfma_f32_16x16x32_bf16 v[118:121], v[130:133], v[198:201], v[118:121]
	v_mfma_f32_16x16x32_bf16 v[114:117], v[158:161], v[198:201], v[114:117]
	v_mfma_f32_16x16x32_bf16 v[110:113], v[130:133], v[206:209], v[110:113]
	v_mfma_f32_16x16x32_bf16 v[106:109], v[158:161], v[206:209], v[106:109]
	v_mfma_f32_16x16x32_bf16 v[102:105], v[130:133], v[214:217], v[102:105]
	v_mfma_f32_16x16x32_bf16 v[98:101], v[158:161], v[214:217], v[98:101]
	v_mfma_f32_16x16x32_bf16 v[126:129], v[134:137], v[194:197], v[126:129]
	v_mfma_f32_16x16x32_bf16 v[122:125], v[170:173], v[194:197], v[122:125]
	v_mfma_f32_16x16x32_bf16 v[118:121], v[134:137], v[202:205], v[118:121]
	v_mfma_f32_16x16x32_bf16 v[114:117], v[170:173], v[202:205], v[114:117]
	v_mfma_f32_16x16x32_bf16 v[110:113], v[134:137], v[210:213], v[110:113]
	v_mfma_f32_16x16x32_bf16 v[106:109], v[170:173], v[210:213], v[106:109]
	v_mfma_f32_16x16x32_bf16 v[102:105], v[134:137], v[218:221], v[102:105]
	v_mfma_f32_16x16x32_bf16 v[98:101], v[170:173], v[218:221], v[98:101]
	v_mfma_f32_16x16x32_bf16 v[62:65], v[174:177], v[190:193], v[62:65]
	v_mfma_f32_16x16x32_bf16 v[58:61], v[182:185], v[190:193], v[58:61]
	v_mfma_f32_16x16x32_bf16 v[54:57], v[174:177], v[198:201], v[54:57]
	v_mfma_f32_16x16x32_bf16 v[50:53], v[182:185], v[198:201], v[50:53]
	v_mfma_f32_16x16x32_bf16 v[46:49], v[174:177], v[206:209], v[46:49]
	v_mfma_f32_16x16x32_bf16 v[42:45], v[182:185], v[206:209], v[42:45]
	v_mfma_f32_16x16x32_bf16 v[38:41], v[174:177], v[214:217], v[38:41]
	v_mfma_f32_16x16x32_bf16 v[34:37], v[182:185], v[214:217], v[34:37]
	v_mfma_f32_16x16x32_bf16 v[62:65], v[178:181], v[194:197], v[62:65]
	v_mfma_f32_16x16x32_bf16 v[58:61], v[186:189], v[194:197], v[58:61]
	v_mfma_f32_16x16x32_bf16 v[54:57], v[178:181], v[202:205], v[54:57]
	v_mfma_f32_16x16x32_bf16 v[50:53], v[186:189], v[202:205], v[50:53]
	v_mfma_f32_16x16x32_bf16 v[46:49], v[178:181], v[210:213], v[46:49]
	v_mfma_f32_16x16x32_bf16 v[42:45], v[186:189], v[210:213], v[42:45]
	v_mfma_f32_16x16x32_bf16 v[38:41], v[178:181], v[218:221], v[38:41]
	v_mfma_f32_16x16x32_bf16 v[34:37], v[186:189], v[218:221], v[34:37]
	s_barrier
	s_add_i32 s46, s62, s22
	s_mov_b32 m0, s46
	ds_read_b128 v[190:193], v168 offset:16384
	ds_read_b128 v[194:197], v168 offset:17408
	ds_read_b128 v[198:201], v168 offset:18432
	ds_read_b128 v[202:205], v168 offset:19456
	ds_read_b128 v[206:209], v168 offset:20480
	ds_read_b128 v[210:213], v168 offset:21504
	ds_read_b128 v[214:217], v168 offset:22528
	ds_read_b128 v[218:221], v168 offset:23552
	global_load_lds_dwordx4 v142, s[14:15]
	s_add_i32 m0, s46, 0x2000
	s_add_u32 s46, s14, 0x4000
	s_addc_u32 s47, s15, 0
	s_add_i32 s48, s35, s22
	global_load_lds_dwordx4 v138, s[14:15]
	s_mov_b32 m0, s48
	s_nop 0
	global_load_lds_dwordx4 v142, s[46:47]
	s_add_i32 m0, s48, 0x2000
	s_nop 0
	global_load_lds_dwordx4 v138, s[46:47]
	s_waitcnt vmcnt(6)
	s_waitcnt lgkmcnt(0)
	s_barrier
	s_waitcnt lgkmcnt(0)
	v_mfma_f32_16x16x32_bf16 v[94:97], v[130:133], v[190:193], v[94:97]
	v_mfma_f32_16x16x32_bf16 v[90:93], v[158:161], v[190:193], v[90:93]
	v_mfma_f32_16x16x32_bf16 v[86:89], v[130:133], v[198:201], v[86:89]
	v_mfma_f32_16x16x32_bf16 v[82:85], v[158:161], v[198:201], v[82:85]
	v_mfma_f32_16x16x32_bf16 v[78:81], v[130:133], v[206:209], v[78:81]
	v_mfma_f32_16x16x32_bf16 v[74:77], v[158:161], v[206:209], v[74:77]
	v_mfma_f32_16x16x32_bf16 v[70:73], v[130:133], v[214:217], v[70:73]
	v_mfma_f32_16x16x32_bf16 v[66:69], v[158:161], v[214:217], v[66:69]
	v_mfma_f32_16x16x32_bf16 v[94:97], v[134:137], v[194:197], v[94:97]
	v_mfma_f32_16x16x32_bf16 v[90:93], v[170:173], v[194:197], v[90:93]
	v_mfma_f32_16x16x32_bf16 v[86:89], v[134:137], v[202:205], v[86:89]
	v_mfma_f32_16x16x32_bf16 v[82:85], v[170:173], v[202:205], v[82:85]
	v_mfma_f32_16x16x32_bf16 v[78:81], v[134:137], v[210:213], v[78:81]
	v_mfma_f32_16x16x32_bf16 v[74:77], v[170:173], v[210:213], v[74:77]
	v_mfma_f32_16x16x32_bf16 v[70:73], v[134:137], v[218:221], v[70:73]
	v_mfma_f32_16x16x32_bf16 v[66:69], v[170:173], v[218:221], v[66:69]
	v_mfma_f32_16x16x32_bf16 v[30:33], v[174:177], v[190:193], v[30:33]
	v_mfma_f32_16x16x32_bf16 v[26:29], v[182:185], v[190:193], v[26:29]
	v_mfma_f32_16x16x32_bf16 v[22:25], v[174:177], v[198:201], v[22:25]
	v_mfma_f32_16x16x32_bf16 v[18:21], v[182:185], v[198:201], v[18:21]
	v_mfma_f32_16x16x32_bf16 v[14:17], v[174:177], v[206:209], v[14:17]
	v_mfma_f32_16x16x32_bf16 v[10:13], v[182:185], v[206:209], v[10:13]
	v_mfma_f32_16x16x32_bf16 v[6:9], v[174:177], v[214:217], v[6:9]
	v_mfma_f32_16x16x32_bf16 v[2:5], v[182:185], v[214:217], v[2:5]
	v_mfma_f32_16x16x32_bf16 v[30:33], v[178:181], v[194:197], v[30:33]
	v_mfma_f32_16x16x32_bf16 v[26:29], v[186:189], v[194:197], v[26:29]
	v_mfma_f32_16x16x32_bf16 v[22:25], v[178:181], v[202:205], v[22:25]
	v_mfma_f32_16x16x32_bf16 v[18:21], v[186:189], v[202:205], v[18:21]
	v_mfma_f32_16x16x32_bf16 v[14:17], v[178:181], v[210:213], v[14:17]
	v_mfma_f32_16x16x32_bf16 v[10:13], v[186:189], v[210:213], v[10:13]
	v_mfma_f32_16x16x32_bf16 v[6:9], v[178:181], v[218:221], v[6:9]
	v_mfma_f32_16x16x32_bf16 v[2:5], v[186:189], v[218:221], v[2:5]
	s_barrier
; #define PG8_STAGE(bufoff, gbase, voff) do { _Pragma("unroll") for (int _i = 0; _i < 2; ++_i) \
;         __builtin_amdgcn_global_load_lds((const unsigned*)((const char*)(gbase) + (voff)[_i]), (LAS unsigned*)(lds + (bufoff) + ldsw + _i * 8192), 16, 0, 0); } while (0)
; #define PG8_LDA(dst, b, h) do { _Pragma("unroll") for (int m = 0; m < 4; ++m) _Pragma("unroll") for (int k = 0; k < 2; ++k) dst[m][k] = *(const LAS bf16x8*)(lds + PG8_SA(b, h) + aoff + m * 2048 + k * 1024); } while (0)
; #define PG8_LDB(dst, b, h) do { _Pragma("unroll") for (int n = 0; n < 2; ++n) _Pragma("unroll") for (int k = 0; k < 2; ++k) dst[n][k] = *(const LAS bf16x8*)(lds + PG8_SB(b, h) + boff + n * 2048 + k * 1024); } while (0)
; #define PG8_WAIT_V(n) asm volatile("s_waitcnt vmcnt(" #n ")" ::: "memory")
; template <class Epi, class Sched, bool I8 = false>
; __device__ __forceinline__ void gemm_phase(LAS unsigned char* lds, const Gemm g, const Sched& S, const Epi& E) {
;     ...
;         for (int t = 0; t < nt; t += 2) {
;             const bool last = (t == nt - 2);
;             const char* a1 = cA + (size_t)(t + 1) * kstep;
;             const char* a2 = last ? nA : cA + (size_t)(t + 2) * kstep; const char* b2 = last ? nB : cB + (size_t)(t + 2) * kstep;
;             const char* a3 = a2 + kstep; const char* b3 = b2 + kstep;
;             PG8_LDB(B0, 0, 0); PG8_LDB(B1, 0, 1); PG8_SCHED; PG8_LDA(At, 0, 0); PG8_STAGE(PG8_SA(1, 1), a1 + hstepA, voffA);
;             PG8_WAIT_V(8); PG8_WAIT_L(0); PG8_BAR; PG8_MMA(0, 0, At, B0); PG8_MMA(0, 1, At, B1); PG8_BAR; PG8_SCHED;
;             PG8_LDA(At, 0, 1); PG8_STAGE(PG8_SB(0, 0), b2, voffB); PG8_STAGE(PG8_SB(0, 1), b2 + hstepB, voffB); PG8_STAGE(PG8_SA(0, 0), a2, voffA);
;             PG8_WAIT_V(8); PG8_WAIT_L(0); PG8_BAR; PG8_MMA(1, 0, At, B0); PG8_MMA(1, 1, At, B1); PG8_BAR; PG8_SCHED;
;             PG8_LDB(B0, 1, 0); PG8_LDB(B1, 1, 1); PG8_SCHED; PG8_LDA(At, 1, 0); PG8_STAGE(PG8_SA(0, 1), a2 + hstepA, voffA);
;             PG8_WAIT_V(8); PG8_WAIT_L(0); PG8_BAR; PG8_MMA(0, 0, At, B0); PG8_MMA(0, 1, At, B1); PG8_BAR; PG8_SCHED;
;             PG8_LDA(At, 1, 1); PG8_STAGE(PG8_SB(1, 0), b3, voffB); PG8_STAGE(PG8_SB(1, 1), b3 + hstepB, voffB); PG8_STAGE(PG8_SA(1, 0), a3, voffA);
;             PG8_WAIT_V(8); PG8_WAIT_L(0); PG8_BAR; PG8_MMA(1, 0, At, B0); PG8_MMA(1, 1, At, B1); PG8_BAR; PG8_SCHED;
;         }
;         if (wr == 0) PG8_BAR;
	s_add_i32 s46, 0, 0x18000
	v_add_u32_e32 v155, s46, v165
	s_add_i32 s47, 0, 0x1c000
	ds_read_b128 v[130:133], v155
	ds_read_b128 v[134:137], v155 offset:1024
	ds_read_b128 v[158:161], v155 offset:2048
	ds_read_b128 v[170:173], v155 offset:3072
	v_add_u32_e32 v155, s47, v165
	ds_read_b128 v[174:177], v155
	ds_read_b128 v[178:181], v155 offset:1024
	ds_read_b128 v[182:185], v155 offset:2048
	ds_read_b128 v[186:189], v155 offset:3072
	s_mov_b32 m0, s26
	s_nop 0
	global_load_lds_dwordx4 v144, s[16:17]
	s_mov_b32 m0, s27
	s_nop 0
	global_load_lds_dwordx4 v140, s[16:17]
	s_add_u32 s16, s16, 0x4000
	s_addc_u32 s17, s17, 0
	s_mov_b32 m0, s28
	ds_read_b128 v[190:193], v168 offset:32768
	ds_read_b128 v[194:197], v168 offset:33792
	ds_read_b128 v[198:201], v168 offset:34816
	ds_read_b128 v[202:205], v168 offset:35840
	ds_read_b128 v[206:209], v168 offset:36864
	ds_read_b128 v[210:213], v168 offset:37888
	ds_read_b128 v[214:217], v168 offset:38912
	ds_read_b128 v[218:221], v168 offset:39936
	global_load_lds_dwordx4 v144, s[16:17]
	s_mov_b32 m0, s29
	s_nop 0
	global_load_lds_dwordx4 v140, s[16:17]
	s_waitcnt vmcnt(8)
	s_waitcnt lgkmcnt(0)
	s_barrier
	s_waitcnt lgkmcnt(0)
	v_mfma_f32_16x16x32_bf16 v[126:129], v[130:133], v[190:193], v[126:129]
	v_mfma_f32_16x16x32_bf16 v[122:125], v[158:161], v[190:193], v[122:125]
	v_mfma_f32_16x16x32_bf16 v[118:121], v[130:133], v[198:201], v[118:121]
	v_mfma_f32_16x16x32_bf16 v[114:117], v[158:161], v[198:201], v[114:117]
	v_mfma_f32_16x16x32_bf16 v[110:113], v[130:133], v[206:209], v[110:113]
	v_mfma_f32_16x16x32_bf16 v[106:109], v[158:161], v[206:209], v[106:109]
	v_mfma_f32_16x16x32_bf16 v[102:105], v[130:133], v[214:217], v[102:105]
	v_mfma_f32_16x16x32_bf16 v[98:101], v[158:161], v[214:217], v[98:101]
	v_mfma_f32_16x16x32_bf16 v[126:129], v[134:137], v[194:197], v[126:129]
	v_mfma_f32_16x16x32_bf16 v[122:125], v[170:173], v[194:197], v[122:125]
	v_mfma_f32_16x16x32_bf16 v[118:121], v[134:137], v[202:205], v[118:121]
	v_mfma_f32_16x16x32_bf16 v[114:117], v[170:173], v[202:205], v[114:117]
	v_mfma_f32_16x16x32_bf16 v[110:113], v[134:137], v[210:213], v[110:113]
	v_mfma_f32_16x16x32_bf16 v[106:109], v[170:173], v[210:213], v[106:109]
	v_mfma_f32_16x16x32_bf16 v[102:105], v[134:137], v[218:221], v[102:105]
	v_mfma_f32_16x16x32_bf16 v[98:101], v[170:173], v[218:221], v[98:101]
	v_mfma_f32_16x16x32_bf16 v[62:65], v[174:177], v[190:193], v[62:65]
	v_mfma_f32_16x16x32_bf16 v[58:61], v[182:185], v[190:193], v[58:61]
	v_mfma_f32_16x16x32_bf16 v[54:57], v[174:177], v[198:201], v[54:57]
	v_mfma_f32_16x16x32_bf16 v[50:53], v[182:185], v[198:201], v[50:53]
	v_mfma_f32_16x16x32_bf16 v[46:49], v[174:177], v[206:209], v[46:49]
	v_mfma_f32_16x16x32_bf16 v[42:45], v[182:185], v[206:209], v[42:45]
	v_mfma_f32_16x16x32_bf16 v[38:41], v[174:177], v[214:217], v[38:41]
	v_mfma_f32_16x16x32_bf16 v[34:37], v[182:185], v[214:217], v[34:37]
	v_mfma_f32_16x16x32_bf16 v[62:65], v[178:181], v[194:197], v[62:65]
	v_mfma_f32_16x16x32_bf16 v[58:61], v[186:189], v[194:197], v[58:61]
	v_mfma_f32_16x16x32_bf16 v[54:57], v[178:181], v[202:205], v[54:57]
	v_mfma_f32_16x16x32_bf16 v[50:53], v[186:189], v[202:205], v[50:53]
	v_mfma_f32_16x16x32_bf16 v[46:49], v[178:181], v[210:213], v[46:49]
	v_mfma_f32_16x16x32_bf16 v[42:45], v[186:189], v[210:213], v[42:45]
	v_mfma_f32_16x16x32_bf16 v[38:41], v[178:181], v[218:221], v[38:41]
	v_mfma_f32_16x16x32_bf16 v[34:37], v[186:189], v[218:221], v[34:37]
	s_barrier
	s_add_u32 s16, s14, 0x8000
	s_addc_u32 s17, s15, 0
	s_add_i32 s46, s46, s22
	s_mov_b32 m0, s46
	ds_read_b128 v[190:193], v168 offset:49152
	ds_read_b128 v[194:197], v168 offset:50176
	ds_read_b128 v[198:201], v168 offset:51200
	ds_read_b128 v[202:205], v168 offset:52224
	ds_read_b128 v[206:209], v168 offset:53248
	ds_read_b128 v[210:213], v168 offset:54272
	ds_read_b128 v[214:217], v168 offset:55296
	ds_read_b128 v[218:221], v168 offset:56320
	global_load_lds_dwordx4 v142, s[16:17]
	s_add_i32 m0, s46, 0x2000
	s_add_u32 s14, s14, 0xc000
	v_lshl_add_u64 v[162:163], s[16:17], 0, v[138:139]
	s_addc_u32 s15, s15, 0
	s_add_i32 s16, s47, s22
	global_load_lds_dwordx4 v[162:163], off
	s_mov_b32 m0, s16
	s_nop 0
	global_load_lds_dwordx4 v142, s[14:15]
	s_add_i32 m0, s16, 0x2000
	s_nop 0
	global_load_lds_dwordx4 v138, s[14:15]
	s_waitcnt vmcnt(6)
	s_waitcnt lgkmcnt(0)
	s_barrier
	s_waitcnt lgkmcnt(0)
	v_mfma_f32_16x16x32_bf16 v[94:97], v[130:133], v[190:193], v[94:97]
	v_mfma_f32_16x16x32_bf16 v[90:93], v[158:161], v[190:193], v[90:93]
	v_mfma_f32_16x16x32_bf16 v[86:89], v[130:133], v[198:201], v[86:89]
	v_mfma_f32_16x16x32_bf16 v[82:85], v[158:161], v[198:201], v[82:85]
	v_mfma_f32_16x16x32_bf16 v[78:81], v[130:133], v[206:209], v[78:81]
	v_mfma_f32_16x16x32_bf16 v[74:77], v[158:161], v[206:209], v[74:77]
	v_mfma_f32_16x16x32_bf16 v[70:73], v[130:133], v[214:217], v[70:73]
	v_mfma_f32_16x16x32_bf16 v[66:69], v[158:161], v[214:217], v[66:69]
	v_mfma_f32_16x16x32_bf16 v[94:97], v[134:137], v[194:197], v[94:97]
	v_mfma_f32_16x16x32_bf16 v[90:93], v[170:173], v[194:197], v[90:93]
	v_mfma_f32_16x16x32_bf16 v[86:89], v[134:137], v[202:205], v[86:89]
	v_mfma_f32_16x16x32_bf16 v[82:85], v[170:173], v[202:205], v[82:85]
	v_mfma_f32_16x16x32_bf16 v[78:81], v[134:137], v[210:213], v[78:81]
	v_mfma_f32_16x16x32_bf16 v[74:77], v[170:173], v[210:213], v[74:77]
	v_mfma_f32_16x16x32_bf16 v[70:73], v[134:137], v[218:221], v[70:73]
	v_mfma_f32_16x16x32_bf16 v[66:69], v[170:173], v[218:221], v[66:69]
	v_mfma_f32_16x16x32_bf16 v[30:33], v[174:177], v[190:193], v[30:33]
	v_mfma_f32_16x16x32_bf16 v[26:29], v[182:185], v[190:193], v[26:29]
	v_mfma_f32_16x16x32_bf16 v[22:25], v[174:177], v[198:201], v[22:25]
	v_mfma_f32_16x16x32_bf16 v[18:21], v[182:185], v[198:201], v[18:21]
	v_mfma_f32_16x16x32_bf16 v[14:17], v[174:177], v[206:209], v[14:17]
	v_mfma_f32_16x16x32_bf16 v[10:13], v[182:185], v[206:209], v[10:13]
	v_mfma_f32_16x16x32_bf16 v[6:9], v[174:177], v[214:217], v[6:9]
	v_mfma_f32_16x16x32_bf16 v[2:5], v[182:185], v[214:217], v[2:5]
	v_mfma_f32_16x16x32_bf16 v[30:33], v[178:181], v[194:197], v[30:33]
	v_mfma_f32_16x16x32_bf16 v[26:29], v[186:189], v[194:197], v[26:29]
	v_mfma_f32_16x16x32_bf16 v[22:25], v[178:181], v[202:205], v[22:25]
	v_mfma_f32_16x16x32_bf16 v[18:21], v[186:189], v[202:205], v[18:21]
	v_mfma_f32_16x16x32_bf16 v[14:17], v[178:181], v[210:213], v[14:17]
	v_mfma_f32_16x16x32_bf16 v[10:13], v[186:189], v[210:213], v[10:13]
	v_mfma_f32_16x16x32_bf16 v[6:9], v[178:181], v[218:221], v[6:9]
	v_mfma_f32_16x16x32_bf16 v[2:5], v[186:189], v[218:221], v[2:5]
	s_barrier
	s_add_i32 s45, s45, 2
	s_add_u32 s10, s10, 0x10000
	s_addc_u32 s11, s11, 0
	s_add_u32 s43, s43, 0x10000
	s_addc_u32 s44, s44, 0
	s_cmp_gt_u32 s45, 5
	s_cbranch_scc0 .LBB0_2685
	s_and_b64 vcc, exec, s[6:7]
	s_cbranch_vccz .LBB0_2688
	s_barrier

; #define PG8_STAGE(bufoff, gbase, voff) do { _Pragma("unroll") for (int _i = 0; _i < 2; ++_i) \
;         __builtin_amdgcn_global_load_lds((const unsigned*)((const char*)(gbase) + (voff)[_i]), (LAS unsigned*)(lds + (bufoff) + ldsw + _i * 8192), 16, 0, 0); } while (0)
; #define PG8_LDA(dst, b, h) do { _Pragma("unroll") for (int m = 0; m < 4; ++m) _Pragma("unroll") for (int k = 0; k < 2; ++k) dst[m][k] = *(const LAS bf16x8*)(lds + PG8_SA(b, h) + aoff + m * 2048 + k * 1024); } while (0)
; #define PG8_LDB(dst, b, h) do { _Pragma("unroll") for (int n = 0; n < 2; ++n) _Pragma("unroll") for (int k = 0; k < 2; ++k) dst[n][k] = *(const LAS bf16x8*)(lds + PG8_SB(b, h) + boff + n * 2048 + k * 1024); } while (0)
; #define PG8_WAIT_V(n) asm volatile("s_waitcnt vmcnt(" #n ")" ::: "memory")
; #define PG8_WAIT_L(n) asm volatile("s_waitcnt lgkmcnt(" #n ")" ::: "memory")
; #define PG8_BAR __builtin_amdgcn_s_barrier()
; #define PG8_SCHED __builtin_amdgcn_sched_barrier(0)
; template <class Epi, class Sched, bool I8 = false>
; __device__ __forceinline__ void gemm_phase(LAS unsigned char* lds, const Gemm g, const Sched& S, const Epi& E) {
;     ...
;             const bool last = (t == nt - 2);
;             const char* a1 = cA + (size_t)(t + 1) * kstep;
;             const char* a2 = last ? nA : cA + (size_t)(t + 2) * kstep; const char* b2 = last ? nB : cB + (size_t)(t + 2) * kstep;
;             const char* a3 = a2 + kstep; const char* b3 = b2 + kstep;
;             PG8_LDB(B0, 0, 0); PG8_LDB(B1, 0, 1); PG8_SCHED; PG8_LDA(At, 0, 0); PG8_STAGE(PG8_SA(1, 1), a1 + hstepA, voffA);
;             PG8_WAIT_V(8); PG8_WAIT_L(0); PG8_BAR; PG8_MMA(0, 0, At, B0); PG8_MMA(0, 1, At, B1); PG8_BAR; PG8_SCHED;
;             PG8_LDA(At, 0, 1); PG8_STAGE(PG8_SB(0, 0), b2, voffB); PG8_STAGE(PG8_SB(0, 1), b2 + hstepB, voffB); PG8_STAGE(PG8_SA(0, 0), a2, voffA);
;             PG8_WAIT_V(8); PG8_WAIT_L(0); PG8_BAR; PG8_MMA(1, 0, At, B0); PG8_MMA(1, 1, At, B1); PG8_BAR; PG8_SCHED;
.LBB0_3744:
	ds_read_b128 v[130:133], v231
	ds_read_b128 v[134:137], v231 offset:1024
	ds_read_b128 v[138:141], v231 offset:2048
	ds_read_b128 v[142:145], v231 offset:3072
	ds_read_b128 v[146:149], v232
	ds_read_b128 v[150:153], v232 offset:1024
	ds_read_b128 v[154:157], v232 offset:2048
	ds_read_b128 v[158:161], v232 offset:3072
	s_add_u32 s34, s30, 0x4000
	s_addc_u32 s35, s31, 0
	s_cmp_eq_u32 s59, 60
	s_cselect_b32 s38, s23, s34
	s_cselect_b32 s39, s5, s35
	s_cselect_b32 s36, s29, s57
	s_cselect_b32 s37, s21, s58
	s_add_u32 s34, s38, 0x8000
	s_addc_u32 s35, s39, 0
	s_sub_u32 s98, s30, 0x4000
	s_subb_u32 s99, s31, 0
	s_mov_b32 m0, s51
	s_nop 0
	global_load_lds_dwordx4 v194, s[98:99]
	s_mov_b32 m0, s52
	s_nop 0
	global_load_lds_dwordx4 v198, s[98:99]
	s_add_i32 m0, s44, 0xc000
	ds_read_b128 v[162:165], v233
	ds_read_b128 v[166:169], v233 offset:1024
	ds_read_b128 v[170:173], v233 offset:2048
	ds_read_b128 v[174:177], v233 offset:3072
	ds_read_b128 v[178:181], v233 offset:4096
	ds_read_b128 v[182:185], v233 offset:5120
	ds_read_b128 v[186:189], v233 offset:6144
	ds_read_b128 v[190:193], v233 offset:7168
	global_load_lds_dwordx4 v204, s[30:31]
	s_add_i32 m0, s44, 0xe000
	s_nop 0
	global_load_lds_dwordx4 v206, s[30:31]
	s_waitcnt vmcnt(8)
	s_waitcnt lgkmcnt(0)
	s_barrier
	s_waitcnt lgkmcnt(0)
	v_mfma_f32_16x16x32_bf16 v[126:129], v[130:133], v[162:165], v[126:129]
	v_mfma_f32_16x16x32_bf16 v[122:125], v[138:141], v[162:165], v[122:125]
	v_mfma_f32_16x16x32_bf16 v[118:121], v[130:133], v[170:173], v[118:121]
	v_mfma_f32_16x16x32_bf16 v[110:113], v[138:141], v[170:173], v[110:113]
	v_mfma_f32_16x16x32_bf16 v[102:105], v[130:133], v[178:181], v[102:105]
	v_mfma_f32_16x16x32_bf16 v[94:97], v[138:141], v[178:181], v[94:97]
	v_mfma_f32_16x16x32_bf16 v[86:89], v[130:133], v[186:189], v[86:89]
	v_mfma_f32_16x16x32_bf16 v[78:81], v[138:141], v[186:189], v[78:81]
	v_mfma_f32_16x16x32_bf16 v[126:129], v[134:137], v[166:169], v[126:129]
	v_mfma_f32_16x16x32_bf16 v[122:125], v[142:145], v[166:169], v[122:125]
	v_mfma_f32_16x16x32_bf16 v[118:121], v[134:137], v[174:177], v[118:121]
	v_mfma_f32_16x16x32_bf16 v[110:113], v[142:145], v[174:177], v[110:113]
	v_mfma_f32_16x16x32_bf16 v[102:105], v[134:137], v[182:185], v[102:105]
	v_mfma_f32_16x16x32_bf16 v[94:97], v[142:145], v[182:185], v[94:97]
	v_mfma_f32_16x16x32_bf16 v[86:89], v[134:137], v[190:193], v[86:89]
	v_mfma_f32_16x16x32_bf16 v[78:81], v[142:145], v[190:193], v[78:81]
	v_mfma_f32_16x16x32_bf16 v[114:117], v[146:149], v[162:165], v[114:117]
	v_mfma_f32_16x16x32_bf16 v[106:109], v[154:157], v[162:165], v[106:109]
	v_mfma_f32_16x16x32_bf16 v[98:101], v[146:149], v[170:173], v[98:101]
	v_mfma_f32_16x16x32_bf16 v[90:93], v[154:157], v[170:173], v[90:93]
	v_mfma_f32_16x16x32_bf16 v[82:85], v[146:149], v[178:181], v[82:85]
	v_mfma_f32_16x16x32_bf16 v[74:77], v[154:157], v[178:181], v[74:77]
	v_mfma_f32_16x16x32_bf16 v[70:73], v[146:149], v[186:189], v[70:73]
	v_mfma_f32_16x16x32_bf16 v[66:69], v[154:157], v[186:189], v[66:69]
	v_mfma_f32_16x16x32_bf16 v[114:117], v[150:153], v[166:169], v[114:117]
	v_mfma_f32_16x16x32_bf16 v[106:109], v[158:161], v[166:169], v[106:109]
	v_mfma_f32_16x16x32_bf16 v[98:101], v[150:153], v[174:177], v[98:101]
	v_mfma_f32_16x16x32_bf16 v[90:93], v[158:161], v[174:177], v[90:93]
	v_mfma_f32_16x16x32_bf16 v[82:85], v[150:153], v[182:185], v[82:85]
	v_mfma_f32_16x16x32_bf16 v[74:77], v[158:161], v[182:185], v[74:77]
	v_mfma_f32_16x16x32_bf16 v[70:73], v[150:153], v[190:193], v[70:73]
	v_mfma_f32_16x16x32_bf16 v[66:69], v[158:161], v[190:193], v[66:69]
	s_barrier
	s_add_i32 s60, s55, s43
	s_mov_b32 m0, s60
	ds_read_b128 v[162:165], v233 offset:16384
	ds_read_b128 v[166:169], v233 offset:17408
	ds_read_b128 v[170:173], v233 offset:18432
	ds_read_b128 v[174:177], v233 offset:19456
	ds_read_b128 v[178:181], v233 offset:20480
	ds_read_b128 v[182:185], v233 offset:21504
	ds_read_b128 v[186:189], v233 offset:22528
	ds_read_b128 v[190:193], v233 offset:23552
	global_load_lds_dwordx4 v196, s[36:37]
	s_add_i32 m0, s60, 0x2000
	s_add_u32 s60, s36, 0x4000
	s_addc_u32 s61, s37, 0
	s_add_i32 s62, s56, s43
	global_load_lds_dwordx4 v200, s[36:37]
	s_mov_b32 m0, s62
	s_nop 0
	global_load_lds_dwordx4 v196, s[60:61]
	s_add_i32 m0, s62, 0x2000
	s_nop 0
	global_load_lds_dwordx4 v200, s[60:61]
	s_waitcnt vmcnt(6)
	s_waitcnt lgkmcnt(0)
	s_barrier
	s_waitcnt lgkmcnt(0)
	v_mfma_f32_16x16x32_bf16 v[62:65], v[130:133], v[162:165], v[62:65]
	v_mfma_f32_16x16x32_bf16 v[58:61], v[138:141], v[162:165], v[58:61]
	v_mfma_f32_16x16x32_bf16 v[54:57], v[130:133], v[170:173], v[54:57]
	v_mfma_f32_16x16x32_bf16 v[46:49], v[138:141], v[170:173], v[46:49]
	v_mfma_f32_16x16x32_bf16 v[38:41], v[130:133], v[178:181], v[38:41]
	v_mfma_f32_16x16x32_bf16 v[30:33], v[138:141], v[178:181], v[30:33]
	v_mfma_f32_16x16x32_bf16 v[22:25], v[130:133], v[186:189], v[22:25]
	v_mfma_f32_16x16x32_bf16 v[14:17], v[138:141], v[186:189], v[14:17]
	v_mfma_f32_16x16x32_bf16 v[62:65], v[134:137], v[166:169], v[62:65]
	v_mfma_f32_16x16x32_bf16 v[58:61], v[142:145], v[166:169], v[58:61]
	v_mfma_f32_16x16x32_bf16 v[54:57], v[134:137], v[174:177], v[54:57]
	v_mfma_f32_16x16x32_bf16 v[46:49], v[142:145], v[174:177], v[46:49]
	v_mfma_f32_16x16x32_bf16 v[38:41], v[134:137], v[182:185], v[38:41]
	v_mfma_f32_16x16x32_bf16 v[30:33], v[142:145], v[182:185], v[30:33]
	v_mfma_f32_16x16x32_bf16 v[22:25], v[134:137], v[190:193], v[22:25]
	v_mfma_f32_16x16x32_bf16 v[14:17], v[142:145], v[190:193], v[14:17]
	v_mfma_f32_16x16x32_bf16 v[50:53], v[146:149], v[162:165], v[50:53]
	v_mfma_f32_16x16x32_bf16 v[42:45], v[154:157], v[162:165], v[42:45]
	v_mfma_f32_16x16x32_bf16 v[34:37], v[146:149], v[170:173], v[34:37]
	v_mfma_f32_16x16x32_bf16 v[26:29], v[154:157], v[170:173], v[26:29]
	v_mfma_f32_16x16x32_bf16 v[18:21], v[146:149], v[178:181], v[18:21]
	v_mfma_f32_16x16x32_bf16 v[10:13], v[154:157], v[178:181], v[10:13]
	v_mfma_f32_16x16x32_bf16 v[6:9], v[146:149], v[186:189], v[6:9]
	v_mfma_f32_16x16x32_bf16 v[2:5], v[154:157], v[186:189], v[2:5]
	v_mfma_f32_16x16x32_bf16 v[50:53], v[150:153], v[166:169], v[50:53]
	v_mfma_f32_16x16x32_bf16 v[42:45], v[158:161], v[166:169], v[42:45]
	v_mfma_f32_16x16x32_bf16 v[34:37], v[150:153], v[174:177], v[34:37]
	v_mfma_f32_16x16x32_bf16 v[26:29], v[158:161], v[174:177], v[26:29]
	v_mfma_f32_16x16x32_bf16 v[18:21], v[150:153], v[182:185], v[18:21]
	v_mfma_f32_16x16x32_bf16 v[10:13], v[158:161], v[182:185], v[10:13]
	v_mfma_f32_16x16x32_bf16 v[6:9], v[150:153], v[190:193], v[6:9]
	v_mfma_f32_16x16x32_bf16 v[2:5], v[158:161], v[190:193], v[2:5]
	s_barrier
; #define PG8_STAGE(bufoff, gbase, voff) do { _Pragma("unroll") for (int _i = 0; _i < 2; ++_i) \
;         __builtin_amdgcn_global_load_lds((const unsigned*)((const char*)(gbase) + (voff)[_i]), (LAS unsigned*)(lds + (bufoff) + ldsw + _i * 8192), 16, 0, 0); } while (0)
; #define PG8_LDA(dst, b, h) do { _Pragma("unroll") for (int m = 0; m < 4; ++m) _Pragma("unroll") for (int k = 0; k < 2; ++k) dst[m][k] = *(const LAS bf16x8*)(lds + PG8_SA(b, h) + aoff + m * 2048 + k * 1024); } while (0)
; #define PG8_LDB(dst, b, h) do { _Pragma("unroll") for (int n = 0; n < 2; ++n) _Pragma("unroll") for (int k = 0; k < 2; ++k) dst[n][k] = *(const LAS bf16x8*)(lds + PG8_SB(b, h) + boff + n * 2048 + k * 1024); } while (0)
; #define PG8_WAIT_V(n) asm volatile("s_waitcnt vmcnt(" #n ")" ::: "memory")
; template <class Epi, class Sched, bool I8 = false>
; __device__ __forceinline__ void gemm_phase(LAS unsigned char* lds, const Gemm g, const Sched& S, const Epi& E) {
;     ...
;         for (int t = 0; t < nt; t += 2) {
;             const bool last = (t == nt - 2);
;             const char* a1 = cA + (size_t)(t + 1) * kstep;
;             const char* a2 = last ? nA : cA + (size_t)(t + 2) * kstep; const char* b2 = last ? nB : cB + (size_t)(t + 2) * kstep;
;             const char* a3 = a2 + kstep; const char* b3 = b2 + kstep;
;             PG8_LDB(B0, 0, 0); PG8_LDB(B1, 0, 1); PG8_SCHED; PG8_LDA(At, 0, 0); PG8_STAGE(PG8_SA(1, 1), a1 + hstepA, voffA);
;             PG8_WAIT_V(8); PG8_WAIT_L(0); PG8_BAR; PG8_MMA(0, 0, At, B0); PG8_MMA(0, 1, At, B1); PG8_BAR; PG8_SCHED;
;             PG8_LDA(At, 0, 1); PG8_STAGE(PG8_SB(0, 0), b2, voffB); PG8_STAGE(PG8_SB(0, 1), b2 + hstepB, voffB); PG8_STAGE(PG8_SA(0, 0), a2, voffA);
;             PG8_WAIT_V(8); PG8_WAIT_L(0); PG8_BAR; PG8_MMA(1, 0, At, B0); PG8_MMA(1, 1, At, B1); PG8_BAR; PG8_SCHED;
;             PG8_LDB(B0, 1, 0); PG8_LDB(B1, 1, 1); PG8_SCHED; PG8_LDA(At, 1, 0); PG8_STAGE(PG8_SA(0, 1), a2 + hstepA, voffA);
;             PG8_WAIT_V(8); PG8_WAIT_L(0); PG8_BAR; PG8_MMA(0, 0, At, B0); PG8_MMA(0, 1, At, B1); PG8_BAR; PG8_SCHED;
;             PG8_LDA(At, 1, 1); PG8_STAGE(PG8_SB(1, 0), b3, voffB); PG8_STAGE(PG8_SB(1, 1), b3 + hstepB, voffB); PG8_STAGE(PG8_SA(1, 0), a3, voffA);
;             PG8_WAIT_V(8); PG8_WAIT_L(0); PG8_BAR; PG8_MMA(1, 0, At, B0); PG8_MMA(1, 1, At, B1); PG8_BAR; PG8_SCHED;
;         }
;         if (wr == 0) PG8_BAR;
	s_add_i32 s60, 0, 0x18000
	s_add_i32 s61, 0, 0x1c000
	v_add_u32_e32 v142, s60, v230
	v_add_u32_e32 v158, s61, v230
	ds_read_b128 v[130:133], v142
	ds_read_b128 v[134:137], v142 offset:1024
	ds_read_b128 v[138:141], v142 offset:2048
	ds_read_b128 v[142:145], v142 offset:3072
	ds_read_b128 v[146:149], v158
	ds_read_b128 v[150:153], v158 offset:1024
	ds_read_b128 v[154:157], v158 offset:2048
	ds_read_b128 v[158:161], v158 offset:3072
	s_mov_b32 m0, s44
	s_nop 0
	global_load_lds_dwordx4 v194, s[38:39]
	s_mov_b32 m0, s45
	s_nop 0
	global_load_lds_dwordx4 v198, s[38:39]
	s_add_u32 s38, s38, 0x4000
	s_addc_u32 s39, s39, 0
	s_mov_b32 m0, s46
	ds_read_b128 v[162:165], v233 offset:32768
	ds_read_b128 v[166:169], v233 offset:33792
	ds_read_b128 v[170:173], v233 offset:34816
	ds_read_b128 v[174:177], v233 offset:35840
	ds_read_b128 v[178:181], v233 offset:36864
	ds_read_b128 v[182:185], v233 offset:37888
	ds_read_b128 v[186:189], v233 offset:38912
	ds_read_b128 v[190:193], v233 offset:39936
	global_load_lds_dwordx4 v194, s[38:39]
	s_mov_b32 m0, s47
	s_nop 0
	global_load_lds_dwordx4 v198, s[38:39]
	s_waitcnt vmcnt(8)
	s_waitcnt lgkmcnt(0)
	s_barrier
	s_waitcnt lgkmcnt(0)
	v_mfma_f32_16x16x32_bf16 v[126:129], v[130:133], v[162:165], v[126:129]
	v_mfma_f32_16x16x32_bf16 v[122:125], v[138:141], v[162:165], v[122:125]
	v_mfma_f32_16x16x32_bf16 v[118:121], v[130:133], v[170:173], v[118:121]
	v_mfma_f32_16x16x32_bf16 v[110:113], v[138:141], v[170:173], v[110:113]
	v_mfma_f32_16x16x32_bf16 v[102:105], v[130:133], v[178:181], v[102:105]
	v_mfma_f32_16x16x32_bf16 v[94:97], v[138:141], v[178:181], v[94:97]
	v_mfma_f32_16x16x32_bf16 v[86:89], v[130:133], v[186:189], v[86:89]
	v_mfma_f32_16x16x32_bf16 v[78:81], v[138:141], v[186:189], v[78:81]
	v_mfma_f32_16x16x32_bf16 v[126:129], v[134:137], v[166:169], v[126:129]
	v_mfma_f32_16x16x32_bf16 v[122:125], v[142:145], v[166:169], v[122:125]
	v_mfma_f32_16x16x32_bf16 v[118:121], v[134:137], v[174:177], v[118:121]
	v_mfma_f32_16x16x32_bf16 v[110:113], v[142:145], v[174:177], v[110:113]
	v_mfma_f32_16x16x32_bf16 v[102:105], v[134:137], v[182:185], v[102:105]
	v_mfma_f32_16x16x32_bf16 v[94:97], v[142:145], v[182:185], v[94:97]
	v_mfma_f32_16x16x32_bf16 v[86:89], v[134:137], v[190:193], v[86:89]
	v_mfma_f32_16x16x32_bf16 v[78:81], v[142:145], v[190:193], v[78:81]
	v_mfma_f32_16x16x32_bf16 v[114:117], v[146:149], v[162:165], v[114:117]
	v_mfma_f32_16x16x32_bf16 v[106:109], v[154:157], v[162:165], v[106:109]
	v_mfma_f32_16x16x32_bf16 v[98:101], v[146:149], v[170:173], v[98:101]
	v_mfma_f32_16x16x32_bf16 v[90:93], v[154:157], v[170:173], v[90:93]
	v_mfma_f32_16x16x32_bf16 v[82:85], v[146:149], v[178:181], v[82:85]
	v_mfma_f32_16x16x32_bf16 v[74:77], v[154:157], v[178:181], v[74:77]
	v_mfma_f32_16x16x32_bf16 v[70:73], v[146:149], v[186:189], v[70:73]
	v_mfma_f32_16x16x32_bf16 v[66:69], v[154:157], v[186:189], v[66:69]
	v_mfma_f32_16x16x32_bf16 v[114:117], v[150:153], v[166:169], v[114:117]
	v_mfma_f32_16x16x32_bf16 v[106:109], v[158:161], v[166:169], v[106:109]
	v_mfma_f32_16x16x32_bf16 v[98:101], v[150:153], v[174:177], v[98:101]
	v_mfma_f32_16x16x32_bf16 v[90:93], v[158:161], v[174:177], v[90:93]
	v_mfma_f32_16x16x32_bf16 v[82:85], v[150:153], v[182:185], v[82:85]
	v_mfma_f32_16x16x32_bf16 v[74:77], v[158:161], v[182:185], v[74:77]
	v_mfma_f32_16x16x32_bf16 v[70:73], v[150:153], v[190:193], v[70:73]
	v_mfma_f32_16x16x32_bf16 v[66:69], v[158:161], v[190:193], v[66:69]
	s_barrier
	s_add_u32 s38, s36, 0x8000
	s_addc_u32 s39, s37, 0
	s_add_i32 s60, s60, s43
	s_mov_b32 m0, s60
	ds_read_b128 v[162:165], v233 offset:49152
	ds_read_b128 v[166:169], v233 offset:50176
	ds_read_b128 v[170:173], v233 offset:51200
	ds_read_b128 v[174:177], v233 offset:52224
	ds_read_b128 v[178:181], v233 offset:53248
	ds_read_b128 v[182:185], v233 offset:54272
	ds_read_b128 v[186:189], v233 offset:55296
	ds_read_b128 v[190:193], v233 offset:56320
	global_load_lds_dwordx4 v196, s[38:39]
	s_add_i32 m0, s60, 0x2000
	s_add_u32 s36, s36, 0xc000
	v_lshl_add_u64 v[212:213], s[38:39], 0, v[200:201]
	s_addc_u32 s37, s37, 0
	s_add_i32 s38, s61, s43
	global_load_lds_dwordx4 v[212:213], off
	s_mov_b32 m0, s38
	s_nop 0
	global_load_lds_dwordx4 v196, s[36:37]
	s_add_i32 m0, s38, 0x2000
	s_nop 0
	global_load_lds_dwordx4 v200, s[36:37]
	s_waitcnt vmcnt(6)
	s_waitcnt lgkmcnt(0)
	s_barrier
	s_waitcnt lgkmcnt(0)
	v_mfma_f32_16x16x32_bf16 v[62:65], v[130:133], v[162:165], v[62:65]
	v_mfma_f32_16x16x32_bf16 v[58:61], v[138:141], v[162:165], v[58:61]
	v_mfma_f32_16x16x32_bf16 v[54:57], v[130:133], v[170:173], v[54:57]
	v_mfma_f32_16x16x32_bf16 v[46:49], v[138:141], v[170:173], v[46:49]
	v_mfma_f32_16x16x32_bf16 v[38:41], v[130:133], v[178:181], v[38:41]
	v_mfma_f32_16x16x32_bf16 v[30:33], v[138:141], v[178:181], v[30:33]
	v_mfma_f32_16x16x32_bf16 v[22:25], v[130:133], v[186:189], v[22:25]
	v_mfma_f32_16x16x32_bf16 v[14:17], v[138:141], v[186:189], v[14:17]
	v_mfma_f32_16x16x32_bf16 v[62:65], v[134:137], v[166:169], v[62:65]
	v_mfma_f32_16x16x32_bf16 v[58:61], v[142:145], v[166:169], v[58:61]
	v_mfma_f32_16x16x32_bf16 v[54:57], v[134:137], v[174:177], v[54:57]
	v_mfma_f32_16x16x32_bf16 v[46:49], v[142:145], v[174:177], v[46:49]
	v_mfma_f32_16x16x32_bf16 v[38:41], v[134:137], v[182:185], v[38:41]
	v_mfma_f32_16x16x32_bf16 v[30:33], v[142:145], v[182:185], v[30:33]
	v_mfma_f32_16x16x32_bf16 v[22:25], v[134:137], v[190:193], v[22:25]
	v_mfma_f32_16x16x32_bf16 v[14:17], v[142:145], v[190:193], v[14:17]
	v_mfma_f32_16x16x32_bf16 v[50:53], v[146:149], v[162:165], v[50:53]
	v_mfma_f32_16x16x32_bf16 v[42:45], v[154:157], v[162:165], v[42:45]
	v_mfma_f32_16x16x32_bf16 v[34:37], v[146:149], v[170:173], v[34:37]
	v_mfma_f32_16x16x32_bf16 v[26:29], v[154:157], v[170:173], v[26:29]
	v_mfma_f32_16x16x32_bf16 v[18:21], v[146:149], v[178:181], v[18:21]
	v_mfma_f32_16x16x32_bf16 v[10:13], v[154:157], v[178:181], v[10:13]
	v_mfma_f32_16x16x32_bf16 v[6:9], v[146:149], v[186:189], v[6:9]
	v_mfma_f32_16x16x32_bf16 v[2:5], v[154:157], v[186:189], v[2:5]
	v_mfma_f32_16x16x32_bf16 v[50:53], v[150:153], v[166:169], v[50:53]
	v_mfma_f32_16x16x32_bf16 v[42:45], v[158:161], v[166:169], v[42:45]
	v_mfma_f32_16x16x32_bf16 v[34:37], v[150:153], v[174:177], v[34:37]
	v_mfma_f32_16x16x32_bf16 v[26:29], v[158:161], v[174:177], v[26:29]
	v_mfma_f32_16x16x32_bf16 v[18:21], v[150:153], v[182:185], v[18:21]
	v_mfma_f32_16x16x32_bf16 v[10:13], v[158:161], v[182:185], v[10:13]
	v_mfma_f32_16x16x32_bf16 v[6:9], v[150:153], v[190:193], v[6:9]
	v_mfma_f32_16x16x32_bf16 v[2:5], v[158:161], v[190:193], v[2:5]
	s_barrier
	s_add_i32 s59, s59, 2
	s_add_u32 s30, s30, 0x10000
	s_addc_u32 s31, s31, 0
	s_add_u32 s57, s57, 0x10000
	s_addc_u32 s58, s58, 0
	s_cmp_gt_u32 s59, 61
	s_cbranch_scc0 .LBB0_3744
	s_and_b64 vcc, exec, s[6:7]
	s_cbranch_vccz .LBB0_3747
	s_barrier

; #define PG8_STAGE(bufoff, gbase, voff) do { _Pragma("unroll") for (int _i = 0; _i < 2; ++_i) \
;         __builtin_amdgcn_global_load_lds((const unsigned*)((const char*)(gbase) + (voff)[_i]), (LAS unsigned*)(lds + (bufoff) + ldsw + _i * 8192), 16, 0, 0); } while (0)
; #define PG8_LDA(dst, b, h) do { _Pragma("unroll") for (int m = 0; m < 4; ++m) _Pragma("unroll") for (int k = 0; k < 2; ++k) dst[m][k] = *(const LAS bf16x8*)(lds + PG8_SA(b, h) + aoff + m * 2048 + k * 1024); } while (0)
; #define PG8_LDB(dst, b, h) do { _Pragma("unroll") for (int n = 0; n < 2; ++n) _Pragma("unroll") for (int k = 0; k < 2; ++k) dst[n][k] = *(const LAS bf16x8*)(lds + PG8_SB(b, h) + boff + n * 2048 + k * 1024); } while (0)
; #define PG8_WAIT_V(n) asm volatile("s_waitcnt vmcnt(" #n ")" ::: "memory")
; #define PG8_WAIT_L(n) asm volatile("s_waitcnt lgkmcnt(" #n ")" ::: "memory")
; #define PG8_BAR __builtin_amdgcn_s_barrier()
; #define PG8_SCHED __builtin_amdgcn_sched_barrier(0)
; template <class Epi, class Sched, bool I8 = false>
; __device__ __forceinline__ void gemm_phase(LAS unsigned char* lds, const Gemm g, const Sched& S, const Epi& E) {
;     ...
;             const bool last = (t == nt - 2);
;             const char* a1 = cA + (size_t)(t + 1) * kstep;
;             const char* a2 = last ? nA : cA + (size_t)(t + 2) * kstep; const char* b2 = last ? nB : cB + (size_t)(t + 2) * kstep;
;             const char* a3 = a2 + kstep; const char* b3 = b2 + kstep;
;             PG8_LDB(B0, 0, 0); PG8_LDB(B1, 0, 1); PG8_SCHED; PG8_LDA(At, 0, 0); PG8_STAGE(PG8_SA(1, 1), a1 + hstepA, voffA);
;             PG8_WAIT_V(8); PG8_WAIT_L(0); PG8_BAR; PG8_MMA(0, 0, At, B0); PG8_MMA(0, 1, At, B1); PG8_BAR; PG8_SCHED;
;             PG8_LDA(At, 0, 1); PG8_STAGE(PG8_SB(0, 0), b2, voffB); PG8_STAGE(PG8_SB(0, 1), b2 + hstepB, voffB); PG8_STAGE(PG8_SA(0, 0), a2, voffA);
;             PG8_WAIT_V(8); PG8_WAIT_L(0); PG8_BAR; PG8_MMA(1, 0, At, B0); PG8_MMA(1, 1, At, B1); PG8_BAR; PG8_SCHED;
.LBB0_4168:
	ds_read_b128 v[66:69], v178
	ds_read_b128 v[70:73], v178 offset:1024
	ds_read_b128 v[74:77], v178 offset:2048
	ds_read_b128 v[78:81], v178 offset:3072
	ds_read_b128 v[146:149], v179
	ds_read_b128 v[150:153], v179 offset:1024
	ds_read_b128 v[172:175], v179 offset:2048
	ds_read_b128 v[182:185], v179 offset:3072
	s_add_u32 s22, s20, 0x4000
	s_addc_u32 s23, s21, 0
	s_cmpk_eq_i32 s51, 0x52
	s_cselect_b32 s26, s0, s22
	s_cselect_b32 s27, s1, s23
	s_cselect_b32 s24, s18, s49
	s_cselect_b32 s25, s19, s50
	s_add_u32 s22, s26, 0x8000
	s_addc_u32 s23, s27, 0
	s_sub_u32 s98, s20, 0x4000
	s_subb_u32 s99, s21, 0
	s_mov_b32 m0, s39
	s_nop 0
	global_load_lds_dwordx4 v154, s[98:99]
	s_mov_b32 m0, s40
	s_nop 0
	global_load_lds_dwordx4 v158, s[98:99]
	s_add_i32 m0, s34, 0xc000
	ds_read_b128 v[186:189], v180
	ds_read_b128 v[190:193], v180 offset:1024
	ds_read_b128 v[194:197], v180 offset:2048
	ds_read_b128 v[198:201], v180 offset:3072
	ds_read_b128 v[202:205], v180 offset:4096
	ds_read_b128 v[206:209], v180 offset:5120
	ds_read_b128 v[210:213], v180 offset:6144
	ds_read_b128 v[214:217], v180 offset:7168
	global_load_lds_dwordx4 v164, s[20:21]
	s_add_i32 m0, s34, 0xe000
	s_nop 0
	global_load_lds_dwordx4 v166, s[20:21]
	s_waitcnt vmcnt(8)
	s_waitcnt lgkmcnt(0)
	s_barrier
	s_waitcnt lgkmcnt(0)
	v_mfma_i32_16x16x64_i8 v[142:145], v[66:69], v[186:189], v[142:145]
	v_mfma_i32_16x16x64_i8 v[138:141], v[74:77], v[186:189], v[138:141]
	v_mfma_i32_16x16x64_i8 v[126:129], v[66:69], v[194:197], v[126:129]
	v_mfma_i32_16x16x64_i8 v[122:125], v[74:77], v[194:197], v[122:125]
	v_mfma_i32_16x16x64_i8 v[110:113], v[66:69], v[202:205], v[110:113]
	v_mfma_i32_16x16x64_i8 v[106:109], v[74:77], v[202:205], v[106:109]
	v_mfma_i32_16x16x64_i8 v[94:97], v[66:69], v[210:213], v[94:97]
	v_mfma_i32_16x16x64_i8 v[90:93], v[74:77], v[210:213], v[90:93]
	v_mfma_i32_16x16x64_i8 v[142:145], v[70:73], v[190:193], v[142:145]
	v_mfma_i32_16x16x64_i8 v[138:141], v[78:81], v[190:193], v[138:141]
	v_mfma_i32_16x16x64_i8 v[126:129], v[70:73], v[198:201], v[126:129]
	v_mfma_i32_16x16x64_i8 v[122:125], v[78:81], v[198:201], v[122:125]
	v_mfma_i32_16x16x64_i8 v[110:113], v[70:73], v[206:209], v[110:113]
	v_mfma_i32_16x16x64_i8 v[106:109], v[78:81], v[206:209], v[106:109]
	v_mfma_i32_16x16x64_i8 v[94:97], v[70:73], v[214:217], v[94:97]
	v_mfma_i32_16x16x64_i8 v[90:93], v[78:81], v[214:217], v[90:93]
	v_mfma_i32_16x16x64_i8 v[134:137], v[146:149], v[186:189], v[134:137]
	v_mfma_i32_16x16x64_i8 v[130:133], v[172:175], v[186:189], v[130:133]
	v_mfma_i32_16x16x64_i8 v[118:121], v[146:149], v[194:197], v[118:121]
	v_mfma_i32_16x16x64_i8 v[114:117], v[172:175], v[194:197], v[114:117]
	v_mfma_i32_16x16x64_i8 v[102:105], v[146:149], v[202:205], v[102:105]
	v_mfma_i32_16x16x64_i8 v[98:101], v[172:175], v[202:205], v[98:101]
	v_mfma_i32_16x16x64_i8 v[86:89], v[146:149], v[210:213], v[86:89]
	v_mfma_i32_16x16x64_i8 v[82:85], v[172:175], v[210:213], v[82:85]
	v_mfma_i32_16x16x64_i8 v[134:137], v[150:153], v[190:193], v[134:137]
	v_mfma_i32_16x16x64_i8 v[130:133], v[182:185], v[190:193], v[130:133]
	v_mfma_i32_16x16x64_i8 v[118:121], v[150:153], v[198:201], v[118:121]
	v_mfma_i32_16x16x64_i8 v[114:117], v[182:185], v[198:201], v[114:117]
	v_mfma_i32_16x16x64_i8 v[102:105], v[150:153], v[206:209], v[102:105]
	v_mfma_i32_16x16x64_i8 v[98:101], v[182:185], v[206:209], v[98:101]
	v_mfma_i32_16x16x64_i8 v[86:89], v[150:153], v[214:217], v[86:89]
	v_mfma_i32_16x16x64_i8 v[82:85], v[182:185], v[214:217], v[82:85]
	s_barrier
	s_add_i32 s52, s43, s33
	s_mov_b32 m0, s52
	ds_read_b128 v[186:189], v180 offset:16384
	ds_read_b128 v[190:193], v180 offset:17408
	ds_read_b128 v[194:197], v180 offset:18432
	ds_read_b128 v[198:201], v180 offset:19456
	ds_read_b128 v[202:205], v180 offset:20480
	ds_read_b128 v[206:209], v180 offset:21504
	ds_read_b128 v[210:213], v180 offset:22528
	ds_read_b128 v[214:217], v180 offset:23552
	global_load_lds_dwordx4 v156, s[24:25]
	s_add_i32 m0, s52, 0x2000
	s_add_u32 s52, s24, 0x4000
	s_addc_u32 s53, s25, 0
	s_add_i32 s54, s44, s33
	global_load_lds_dwordx4 v160, s[24:25]
	s_mov_b32 m0, s54
	s_nop 0
	global_load_lds_dwordx4 v156, s[52:53]
	s_add_i32 m0, s54, 0x2000
	s_nop 0
	global_load_lds_dwordx4 v160, s[52:53]
	s_waitcnt vmcnt(6)
	s_waitcnt lgkmcnt(0)
	s_barrier
	s_waitcnt lgkmcnt(0)
	v_mfma_i32_16x16x64_i8 v[62:65], v[66:69], v[186:189], v[62:65]
	v_mfma_i32_16x16x64_i8 v[58:61], v[74:77], v[186:189], v[58:61]
	v_mfma_i32_16x16x64_i8 v[46:49], v[66:69], v[194:197], v[46:49]
	v_mfma_i32_16x16x64_i8 v[42:45], v[74:77], v[194:197], v[42:45]
	v_mfma_i32_16x16x64_i8 v[30:33], v[66:69], v[202:205], v[30:33]
	v_mfma_i32_16x16x64_i8 v[26:29], v[74:77], v[202:205], v[26:29]
	v_mfma_i32_16x16x64_i8 v[14:17], v[66:69], v[210:213], v[14:17]
	v_mfma_i32_16x16x64_i8 v[10:13], v[74:77], v[210:213], v[10:13]
	v_mfma_i32_16x16x64_i8 v[62:65], v[70:73], v[190:193], v[62:65]
	v_mfma_i32_16x16x64_i8 v[58:61], v[78:81], v[190:193], v[58:61]
	v_mfma_i32_16x16x64_i8 v[46:49], v[70:73], v[198:201], v[46:49]
	v_mfma_i32_16x16x64_i8 v[42:45], v[78:81], v[198:201], v[42:45]
	v_mfma_i32_16x16x64_i8 v[30:33], v[70:73], v[206:209], v[30:33]
	v_mfma_i32_16x16x64_i8 v[26:29], v[78:81], v[206:209], v[26:29]
	v_mfma_i32_16x16x64_i8 v[14:17], v[70:73], v[214:217], v[14:17]
	v_mfma_i32_16x16x64_i8 v[10:13], v[78:81], v[214:217], v[10:13]
	v_mfma_i32_16x16x64_i8 v[54:57], v[146:149], v[186:189], v[54:57]
	v_mfma_i32_16x16x64_i8 v[50:53], v[172:175], v[186:189], v[50:53]
	v_mfma_i32_16x16x64_i8 v[38:41], v[146:149], v[194:197], v[38:41]
	v_mfma_i32_16x16x64_i8 v[34:37], v[172:175], v[194:197], v[34:37]
	v_mfma_i32_16x16x64_i8 v[22:25], v[146:149], v[202:205], v[22:25]
	v_mfma_i32_16x16x64_i8 v[18:21], v[172:175], v[202:205], v[18:21]
	v_mfma_i32_16x16x64_i8 v[6:9], v[146:149], v[210:213], v[6:9]
	v_mfma_i32_16x16x64_i8 v[2:5], v[172:175], v[210:213], v[2:5]
	v_mfma_i32_16x16x64_i8 v[54:57], v[150:153], v[190:193], v[54:57]
	v_mfma_i32_16x16x64_i8 v[50:53], v[182:185], v[190:193], v[50:53]
	v_mfma_i32_16x16x64_i8 v[38:41], v[150:153], v[198:201], v[38:41]
	v_mfma_i32_16x16x64_i8 v[34:37], v[182:185], v[198:201], v[34:37]
	v_mfma_i32_16x16x64_i8 v[22:25], v[150:153], v[206:209], v[22:25]
	v_mfma_i32_16x16x64_i8 v[18:21], v[182:185], v[206:209], v[18:21]
	v_mfma_i32_16x16x64_i8 v[6:9], v[150:153], v[214:217], v[6:9]
	v_mfma_i32_16x16x64_i8 v[2:5], v[182:185], v[214:217], v[2:5]
	s_barrier
; #define PG8_STAGE(bufoff, gbase, voff) do { _Pragma("unroll") for (int _i = 0; _i < 2; ++_i) \
;         __builtin_amdgcn_global_load_lds((const unsigned*)((const char*)(gbase) + (voff)[_i]), (LAS unsigned*)(lds + (bufoff) + ldsw + _i * 8192), 16, 0, 0); } while (0)
; #define PG8_LDA(dst, b, h) do { _Pragma("unroll") for (int m = 0; m < 4; ++m) _Pragma("unroll") for (int k = 0; k < 2; ++k) dst[m][k] = *(const LAS bf16x8*)(lds + PG8_SA(b, h) + aoff + m * 2048 + k * 1024); } while (0)
; #define PG8_LDB(dst, b, h) do { _Pragma("unroll") for (int n = 0; n < 2; ++n) _Pragma("unroll") for (int k = 0; k < 2; ++k) dst[n][k] = *(const LAS bf16x8*)(lds + PG8_SB(b, h) + boff + n * 2048 + k * 1024); } while (0)
; #define PG8_WAIT_V(n) asm volatile("s_waitcnt vmcnt(" #n ")" ::: "memory")
; template <class Epi, class Sched, bool I8 = false>
; __device__ __forceinline__ void gemm_phase(LAS unsigned char* lds, const Gemm g, const Sched& S, const Epi& E) {
;     ...
;         for (int t = 0; t < nt; t += 2) {
;             const bool last = (t == nt - 2);
;             const char* a1 = cA + (size_t)(t + 1) * kstep;
;             const char* a2 = last ? nA : cA + (size_t)(t + 2) * kstep; const char* b2 = last ? nB : cB + (size_t)(t + 2) * kstep;
;             const char* a3 = a2 + kstep; const char* b3 = b2 + kstep;
;             PG8_LDB(B0, 0, 0); PG8_LDB(B1, 0, 1); PG8_SCHED; PG8_LDA(At, 0, 0); PG8_STAGE(PG8_SA(1, 1), a1 + hstepA, voffA);
;             PG8_WAIT_V(8); PG8_WAIT_L(0); PG8_BAR; PG8_MMA(0, 0, At, B0); PG8_MMA(0, 1, At, B1); PG8_BAR; PG8_SCHED;
;             PG8_LDA(At, 0, 1); PG8_STAGE(PG8_SB(0, 0), b2, voffB); PG8_STAGE(PG8_SB(0, 1), b2 + hstepB, voffB); PG8_STAGE(PG8_SA(0, 0), a2, voffA);
;             PG8_WAIT_V(8); PG8_WAIT_L(0); PG8_BAR; PG8_MMA(1, 0, At, B0); PG8_MMA(1, 1, At, B1); PG8_BAR; PG8_SCHED;
;             PG8_LDB(B0, 1, 0); PG8_LDB(B1, 1, 1); PG8_SCHED; PG8_LDA(At, 1, 0); PG8_STAGE(PG8_SA(0, 1), a2 + hstepA, voffA);
;             PG8_WAIT_V(8); PG8_WAIT_L(0); PG8_BAR; PG8_MMA(0, 0, At, B0); PG8_MMA(0, 1, At, B1); PG8_BAR; PG8_SCHED;
;             PG8_LDA(At, 1, 1); PG8_STAGE(PG8_SB(1, 0), b3, voffB); PG8_STAGE(PG8_SB(1, 1), b3 + hstepB, voffB); PG8_STAGE(PG8_SA(1, 0), a3, voffA);
;             PG8_WAIT_V(8); PG8_WAIT_L(0); PG8_BAR; PG8_MMA(1, 0, At, B0); PG8_MMA(1, 1, At, B1); PG8_BAR; PG8_SCHED;
;         }
;         if (wr == 0) PG8_BAR;
	s_add_i32 s52, 0, 0x18000
	s_add_i32 s53, 0, 0x1c000
	v_add_u32_e32 v78, s52, v176
	v_add_u32_e32 v162, s53, v176
	ds_read_b128 v[66:69], v78
	ds_read_b128 v[70:73], v78 offset:1024
	ds_read_b128 v[74:77], v78 offset:2048
	ds_read_b128 v[78:81], v78 offset:3072
	ds_read_b128 v[146:149], v162
	ds_read_b128 v[150:153], v162 offset:1024
	ds_read_b128 v[172:175], v162 offset:2048
	ds_read_b128 v[182:185], v162 offset:3072
	s_mov_b32 m0, s34
	s_nop 0
	global_load_lds_dwordx4 v154, s[26:27]
	s_mov_b32 m0, s35
	s_nop 0
	global_load_lds_dwordx4 v158, s[26:27]
	s_add_u32 s26, s26, 0x4000
	s_addc_u32 s27, s27, 0
	s_mov_b32 m0, s36
	ds_read_b128 v[186:189], v180 offset:32768
	ds_read_b128 v[190:193], v180 offset:33792
	ds_read_b128 v[194:197], v180 offset:34816
	ds_read_b128 v[198:201], v180 offset:35840
	ds_read_b128 v[202:205], v180 offset:36864
	ds_read_b128 v[206:209], v180 offset:37888
	ds_read_b128 v[210:213], v180 offset:38912
	ds_read_b128 v[214:217], v180 offset:39936
	global_load_lds_dwordx4 v154, s[26:27]
	s_mov_b32 m0, s37
	s_nop 0
	global_load_lds_dwordx4 v158, s[26:27]
	s_waitcnt vmcnt(8)
	s_waitcnt lgkmcnt(0)
	s_barrier
	s_waitcnt lgkmcnt(0)
	v_mfma_i32_16x16x64_i8 v[142:145], v[66:69], v[186:189], v[142:145]
	v_mfma_i32_16x16x64_i8 v[138:141], v[74:77], v[186:189], v[138:141]
	v_mfma_i32_16x16x64_i8 v[126:129], v[66:69], v[194:197], v[126:129]
	v_mfma_i32_16x16x64_i8 v[122:125], v[74:77], v[194:197], v[122:125]
	v_mfma_i32_16x16x64_i8 v[110:113], v[66:69], v[202:205], v[110:113]
	v_mfma_i32_16x16x64_i8 v[106:109], v[74:77], v[202:205], v[106:109]
	v_mfma_i32_16x16x64_i8 v[94:97], v[66:69], v[210:213], v[94:97]
	v_mfma_i32_16x16x64_i8 v[90:93], v[74:77], v[210:213], v[90:93]
	v_mfma_i32_16x16x64_i8 v[142:145], v[70:73], v[190:193], v[142:145]
	v_mfma_i32_16x16x64_i8 v[138:141], v[78:81], v[190:193], v[138:141]
	v_mfma_i32_16x16x64_i8 v[126:129], v[70:73], v[198:201], v[126:129]
	v_mfma_i32_16x16x64_i8 v[122:125], v[78:81], v[198:201], v[122:125]
	v_mfma_i32_16x16x64_i8 v[110:113], v[70:73], v[206:209], v[110:113]
	v_mfma_i32_16x16x64_i8 v[106:109], v[78:81], v[206:209], v[106:109]
	v_mfma_i32_16x16x64_i8 v[94:97], v[70:73], v[214:217], v[94:97]
	v_mfma_i32_16x16x64_i8 v[90:93], v[78:81], v[214:217], v[90:93]
	v_mfma_i32_16x16x64_i8 v[134:137], v[146:149], v[186:189], v[134:137]
	v_mfma_i32_16x16x64_i8 v[130:133], v[172:175], v[186:189], v[130:133]
	v_mfma_i32_16x16x64_i8 v[118:121], v[146:149], v[194:197], v[118:121]
	v_mfma_i32_16x16x64_i8 v[114:117], v[172:175], v[194:197], v[114:117]
	v_mfma_i32_16x16x64_i8 v[102:105], v[146:149], v[202:205], v[102:105]
	v_mfma_i32_16x16x64_i8 v[98:101], v[172:175], v[202:205], v[98:101]
	v_mfma_i32_16x16x64_i8 v[86:89], v[146:149], v[210:213], v[86:89]
	v_mfma_i32_16x16x64_i8 v[82:85], v[172:175], v[210:213], v[82:85]
	v_mfma_i32_16x16x64_i8 v[134:137], v[150:153], v[190:193], v[134:137]
	v_mfma_i32_16x16x64_i8 v[130:133], v[182:185], v[190:193], v[130:133]
	v_mfma_i32_16x16x64_i8 v[118:121], v[150:153], v[198:201], v[118:121]
	v_mfma_i32_16x16x64_i8 v[114:117], v[182:185], v[198:201], v[114:117]
	v_mfma_i32_16x16x64_i8 v[102:105], v[150:153], v[206:209], v[102:105]
	v_mfma_i32_16x16x64_i8 v[98:101], v[182:185], v[206:209], v[98:101]
	v_mfma_i32_16x16x64_i8 v[86:89], v[150:153], v[214:217], v[86:89]
	v_mfma_i32_16x16x64_i8 v[82:85], v[182:185], v[214:217], v[82:85]
	s_barrier
	s_add_u32 s26, s24, 0x8000
	s_addc_u32 s27, s25, 0
	s_add_i32 s52, s52, s33
	s_mov_b32 m0, s52
	ds_read_b128 v[186:189], v180 offset:49152
	ds_read_b128 v[190:193], v180 offset:50176
	ds_read_b128 v[194:197], v180 offset:51200
	ds_read_b128 v[198:201], v180 offset:52224
	ds_read_b128 v[202:205], v180 offset:53248
	ds_read_b128 v[206:209], v180 offset:54272
	ds_read_b128 v[210:213], v180 offset:55296
	ds_read_b128 v[214:217], v180 offset:56320
	global_load_lds_dwordx4 v156, s[26:27]
	s_add_i32 m0, s52, 0x2000
	s_add_u32 s24, s24, 0xc000
	v_lshl_add_u64 v[218:219], s[26:27], 0, v[160:161]
	s_addc_u32 s25, s25, 0
	s_add_i32 s26, s53, s33
	global_load_lds_dwordx4 v[218:219], off
	s_mov_b32 m0, s26
	s_nop 0
	global_load_lds_dwordx4 v156, s[24:25]
	s_add_i32 m0, s26, 0x2000
	s_nop 0
	global_load_lds_dwordx4 v160, s[24:25]
	s_waitcnt vmcnt(6)
	s_waitcnt lgkmcnt(0)
	s_barrier
	s_waitcnt lgkmcnt(0)
	v_mfma_i32_16x16x64_i8 v[62:65], v[66:69], v[186:189], v[62:65]
	v_mfma_i32_16x16x64_i8 v[58:61], v[74:77], v[186:189], v[58:61]
	v_mfma_i32_16x16x64_i8 v[46:49], v[66:69], v[194:197], v[46:49]
	v_mfma_i32_16x16x64_i8 v[42:45], v[74:77], v[194:197], v[42:45]
	v_mfma_i32_16x16x64_i8 v[30:33], v[66:69], v[202:205], v[30:33]
	v_mfma_i32_16x16x64_i8 v[26:29], v[74:77], v[202:205], v[26:29]
	v_mfma_i32_16x16x64_i8 v[14:17], v[66:69], v[210:213], v[14:17]
	v_mfma_i32_16x16x64_i8 v[10:13], v[74:77], v[210:213], v[10:13]
	v_mfma_i32_16x16x64_i8 v[62:65], v[70:73], v[190:193], v[62:65]
	v_mfma_i32_16x16x64_i8 v[58:61], v[78:81], v[190:193], v[58:61]
	v_mfma_i32_16x16x64_i8 v[46:49], v[70:73], v[198:201], v[46:49]
	v_mfma_i32_16x16x64_i8 v[42:45], v[78:81], v[198:201], v[42:45]
	v_mfma_i32_16x16x64_i8 v[30:33], v[70:73], v[206:209], v[30:33]
	v_mfma_i32_16x16x64_i8 v[26:29], v[78:81], v[206:209], v[26:29]
	v_mfma_i32_16x16x64_i8 v[14:17], v[70:73], v[214:217], v[14:17]
	v_mfma_i32_16x16x64_i8 v[10:13], v[78:81], v[214:217], v[10:13]
	v_mfma_i32_16x16x64_i8 v[54:57], v[146:149], v[186:189], v[54:57]
	v_mfma_i32_16x16x64_i8 v[50:53], v[172:175], v[186:189], v[50:53]
	v_mfma_i32_16x16x64_i8 v[38:41], v[146:149], v[194:197], v[38:41]
	v_mfma_i32_16x16x64_i8 v[34:37], v[172:175], v[194:197], v[34:37]
	v_mfma_i32_16x16x64_i8 v[22:25], v[146:149], v[202:205], v[22:25]
	v_mfma_i32_16x16x64_i8 v[18:21], v[172:175], v[202:205], v[18:21]
	v_mfma_i32_16x16x64_i8 v[6:9], v[146:149], v[210:213], v[6:9]
	v_mfma_i32_16x16x64_i8 v[2:5], v[172:175], v[210:213], v[2:5]
	v_mfma_i32_16x16x64_i8 v[54:57], v[150:153], v[190:193], v[54:57]
	v_mfma_i32_16x16x64_i8 v[50:53], v[182:185], v[190:193], v[50:53]
	v_mfma_i32_16x16x64_i8 v[38:41], v[150:153], v[198:201], v[38:41]
	v_mfma_i32_16x16x64_i8 v[34:37], v[182:185], v[198:201], v[34:37]
	v_mfma_i32_16x16x64_i8 v[22:25], v[150:153], v[206:209], v[22:25]
	v_mfma_i32_16x16x64_i8 v[18:21], v[182:185], v[206:209], v[18:21]
	v_mfma_i32_16x16x64_i8 v[6:9], v[150:153], v[214:217], v[6:9]
	v_mfma_i32_16x16x64_i8 v[2:5], v[182:185], v[214:217], v[2:5]
	s_barrier
	s_add_i32 s51, s51, 2
	s_add_u32 s20, s20, 0x10000
	s_addc_u32 s21, s21, 0
	s_add_u32 s49, s49, 0x10000
	s_addc_u32 s50, s50, 0
	s_cmpk_gt_u32 s51, 0x53
	s_cbranch_scc0 .LBB0_4168
	s_and_b64 vcc, exec, s[14:15]
	s_cbranch_vccz .LBB0_4171
	s_barrier
